# combo9 + remaining reduction ladders (row absmax / sum of squares in the quant passes, row prologue, final norm): ds_swizzle SWAP 1,2,4,8 replaced by exact DPP lane moves; K-loop placement kept
# baseline (speedup 1.0000x reference)
.LBB0_99:
	v_mov_b32_e32 v64, v68
	s_add_u32 s4, s16, s10
	v_lshlrev_b32_e32 v0, 2, v64
	v_ashrrev_i32_e32 v1, 31, v0
	v_lshl_add_u64 v[4:5], v[0:1], 4, s[8:9]
	global_load_dwordx4 v[60:63], v[4:5], off
	global_load_dwordx4 v[56:59], v[4:5], off offset:16
	global_load_dwordx4 v[52:55], v[4:5], off offset:32
	global_load_dwordx4 v[48:51], v[4:5], off offset:48
	v_add_co_u32_e32 v0, vcc, s1, v4
	v_lshl_add_u64 v[2:3], v[4:5], 0, s[18:19]
	s_nop 0
	v_addc_co_u32_e32 v1, vcc, 0, v5, vcc
	global_load_dwordx4 v[32:35], v[0:1], off offset:-4096
	global_load_dwordx4 v[44:47], v[2:3], off offset:16
	global_load_dwordx4 v[40:43], v[2:3], off offset:32
	global_load_dwordx4 v[36:39], v[2:3], off offset:48
	global_load_dwordx4 v[16:19], v[0:1], off
	v_lshl_add_u64 v[0:1], v[4:5], 0, s[20:21]
	global_load_dwordx4 v[28:31], v[0:1], off offset:16
	global_load_dwordx4 v[24:27], v[0:1], off offset:32
	global_load_dwordx4 v[20:23], v[0:1], off offset:48
	v_add_co_u32_e32 v0, vcc, s3, v4
	v_lshl_add_u64 v[66:67], v[4:5], 0, s[22:23]
	s_nop 0
	v_addc_co_u32_e32 v1, vcc, 0, v5, vcc
	global_load_dwordx4 v[0:3], v[0:1], off
	s_nop 0
	global_load_dwordx4 v[12:15], v[66:67], off offset:16
	global_load_dwordx4 v[8:11], v[66:67], off offset:32
	global_load_dwordx4 v[4:7], v[66:67], off offset:48
	v_lshlrev_b32_e32 v66, 1, v64
	v_ashrrev_i32_e32 v67, 31, v66
	s_addc_u32 s5, s17, s11
	v_lshl_add_u64 v[80:81], v[66:67], 4, s[4:5]
	s_waitcnt vmcnt(15)
	v_mul_f32_e32 v73, v61, v61
	v_fmac_f32_e32 v73, v60, v60
	v_fmac_f32_e32 v73, v62, v62
	v_fmac_f32_e32 v73, v63, v63
	s_waitcnt vmcnt(14)
	v_fmac_f32_e32 v73, v56, v56
	v_fmac_f32_e32 v73, v57, v57
	v_fmac_f32_e32 v73, v58, v58
	v_fmac_f32_e32 v73, v59, v59
	v_max3_f32 v65, |v60|, 0, |v61|
	s_waitcnt vmcnt(13)
	v_fmac_f32_e32 v73, v52, v52
	v_max3_f32 v65, v65, |v62|, |v63|
	v_fmac_f32_e32 v73, v53, v53
	v_max3_f32 v65, v65, |v56|, |v57|
	v_fmac_f32_e32 v73, v54, v54
	v_max3_f32 v65, v65, |v58|, |v59|
	v_fmac_f32_e32 v73, v55, v55
	v_max3_f32 v65, v65, |v52|, |v53|
	s_waitcnt vmcnt(12)
	v_fmac_f32_e32 v73, v48, v48
	v_max3_f32 v65, v65, |v54|, |v55|
	v_fmac_f32_e32 v73, v49, v49
	v_max3_f32 v65, v65, |v48|, |v49|
	v_fmac_f32_e32 v73, v50, v50
	v_max3_f32 v65, v65, |v50|, |v51|
	v_fmac_f32_e32 v73, v51, v51
	s_waitcnt vmcnt(11)
	v_max3_f32 v65, v65, |v32|, |v33|
	v_fmac_f32_e32 v73, v32, v32
	v_max3_f32 v65, v65, |v34|, |v35|
	v_fmac_f32_e32 v73, v33, v33
	s_waitcnt vmcnt(10)
	v_max3_f32 v65, v65, |v44|, |v45|
	v_fmac_f32_e32 v73, v34, v34
	v_max3_f32 v65, v65, |v46|, |v47|
	v_fmac_f32_e32 v73, v35, v35
	s_waitcnt vmcnt(9)
	v_max3_f32 v65, v65, |v40|, |v41|
	v_fmac_f32_e32 v73, v44, v44
	v_max3_f32 v65, v65, |v42|, |v43|
	v_fmac_f32_e32 v73, v45, v45
	s_waitcnt vmcnt(8)
	v_max3_f32 v65, v65, |v36|, |v37|
	v_fmac_f32_e32 v73, v46, v46
	v_max3_f32 v65, v65, |v38|, |v39|
	v_fmac_f32_e32 v73, v47, v47
	s_waitcnt vmcnt(7)
	v_max3_f32 v65, v65, |v16|, |v17|
	v_fmac_f32_e32 v73, v40, v40
	v_max3_f32 v65, v65, |v18|, |v19|
	v_fmac_f32_e32 v73, v41, v41
	s_waitcnt vmcnt(6)
	v_max3_f32 v65, v65, |v28|, |v29|
	v_fmac_f32_e32 v73, v42, v42
	v_max3_f32 v65, v65, |v30|, |v31|
	v_fmac_f32_e32 v73, v43, v43
	s_waitcnt vmcnt(5)
	v_max3_f32 v65, v65, |v24|, |v25|
	v_fmac_f32_e32 v73, v36, v36
	v_max3_f32 v65, v65, |v26|, |v27|
	v_fmac_f32_e32 v73, v37, v37
	s_waitcnt vmcnt(4)
	v_max3_f32 v65, v65, |v20|, |v21|
	v_fmac_f32_e32 v73, v38, v38
	v_max3_f32 v65, v65, |v22|, |v23|
	v_fmac_f32_e32 v73, v39, v39
	s_waitcnt vmcnt(3)
	v_max3_f32 v65, v65, |v0|, |v1|
	v_fmac_f32_e32 v73, v16, v16
	v_max3_f32 v65, v65, |v2|, |v3|
	v_fmac_f32_e32 v73, v17, v17
	s_waitcnt vmcnt(2)
	v_max3_f32 v65, v65, |v12|, |v13|
	v_fmac_f32_e32 v73, v18, v18
	v_max3_f32 v65, v65, |v14|, |v15|
	v_fmac_f32_e32 v73, v19, v19
	s_waitcnt vmcnt(1)
	v_max3_f32 v65, v65, |v8|, |v9|
	v_fmac_f32_e32 v73, v28, v28
	v_max3_f32 v65, v65, |v10|, |v11|
	v_fmac_f32_e32 v73, v29, v29
	s_waitcnt vmcnt(0)
	v_max3_f32 v65, v65, |v4|, |v5|
	v_fmac_f32_e32 v73, v30, v30
	v_max3_f32 v65, v65, |v6|, |v7|
	v_fmac_f32_e32 v73, v31, v31
	s_nop 1
	v_mov_b32_dpp v74, v65 quad_perm:[1,0,3,2] row_mask:0xf bank_mask:0xf
	v_fmac_f32_e32 v73, v24, v24
	v_fmac_f32_e32 v73, v25, v25
	v_fmac_f32_e32 v73, v26, v26
	v_fmac_f32_e32 v73, v27, v27
	v_fmac_f32_e32 v73, v20, v20
	s_waitcnt lgkmcnt(0)
	v_max_f32_e32 v74, v74, v74
	v_fmac_f32_e32 v73, v21, v21
	v_max_f32_e32 v65, v65, v74
	v_fmac_f32_e32 v73, v22, v22
	s_nop 1
	v_mov_b32_dpp v74, v65 quad_perm:[2,3,0,1] row_mask:0xf bank_mask:0xf
	v_fmac_f32_e32 v73, v23, v23
	v_fmac_f32_e32 v73, v0, v0
	v_fmac_f32_e32 v73, v1, v1
	v_fmac_f32_e32 v73, v2, v2
	v_fmac_f32_e32 v73, v3, v3
	s_waitcnt lgkmcnt(0)
	v_max_f32_e32 v74, v74, v74
	v_fmac_f32_e32 v73, v12, v12
	v_max_f32_e32 v65, v65, v74
	v_fmac_f32_e32 v73, v13, v13
	s_nop 1
	v_mov_b32_dpp v74, v65 row_shl:4 row_mask:0xf bank_mask:0x5
	v_mov_b32_dpp v74, v65 row_shr:4 row_mask:0xf bank_mask:0xa
	v_fmac_f32_e32 v73, v14, v14
	v_fmac_f32_e32 v73, v15, v15
	v_fmac_f32_e32 v73, v8, v8
	v_fmac_f32_e32 v73, v9, v9
	v_fmac_f32_e32 v73, v10, v10
	s_waitcnt lgkmcnt(0)
	v_max_f32_e32 v74, v74, v74
	v_fmac_f32_e32 v73, v11, v11
	v_max_f32_e32 v65, v65, v74
	v_fmac_f32_e32 v73, v4, v4
	s_nop 1
	v_mov_b32_dpp v74, v65 row_ror:8 row_mask:0xf bank_mask:0xf
	v_fmac_f32_e32 v73, v5, v5
	v_fmac_f32_e32 v73, v6, v6
	v_fmac_f32_e32 v73, v7, v7
	s_nop 1
	v_mov_b32_dpp v75, v73 quad_perm:[1,0,3,2] row_mask:0xf bank_mask:0xf
	s_waitcnt lgkmcnt(0)
	v_max_f32_e32 v74, v74, v74
	v_max_f32_e32 v65, v65, v74
	ds_swizzle_b32 v74, v65 offset:swizzle(SWAP,16)
	s_waitcnt lgkmcnt(0)
	v_add_f32_e32 v75, v73, v75
	s_nop 1
	v_mov_b32_dpp v76, v75 quad_perm:[2,3,0,1] row_mask:0xf bank_mask:0xf
	s_waitcnt lgkmcnt(0)
	v_max_f32_e32 v74, v74, v74
	v_max_f32_e32 v65, v65, v74
	v_mov_b32_e32 v74, v65
	s_waitcnt lgkmcnt(0)
	v_add_f32_e32 v75, v75, v76
	v_permlane32_swap_b32_e32 v65, v74
	s_nop 1
	v_mov_b32_dpp v76, v75 row_shl:4 row_mask:0xf bank_mask:0x5
	v_mov_b32_dpp v76, v75 row_shr:4 row_mask:0xf bank_mask:0xa
	v_max_f32_e32 v74, v74, v74
	v_max_f32_e32 v65, v65, v65
	v_max_f32_e32 v73, v65, v74
	v_div_scale_f32 v65, s[30:31], v73, v73, s27
	v_rcp_f32_e32 v74, v65
	s_waitcnt lgkmcnt(0)
	v_add_f32_e32 v75, v75, v76
	s_nop 1
	v_mov_b32_dpp v76, v75 row_ror:8 row_mask:0xf bank_mask:0xf
	v_div_scale_f32 v77, vcc, s27, v73, s27
	v_fma_f32 v78, -v65, v74, 1.0
	v_fmac_f32_e32 v74, v78, v74
	v_mul_f32_e32 v78, v77, v74
	v_fma_f32 v79, -v65, v78, v77
	s_waitcnt lgkmcnt(0)
	v_add_f32_e32 v75, v75, v76
	v_fmac_f32_e32 v78, v79, v74
	ds_swizzle_b32 v76, v75 offset:swizzle(SWAP,16)
	v_fma_f32 v65, -v65, v78, v77
	v_div_fmas_f32 v65, v65, v74, v78
	v_div_fixup_f32 v65, v65, v73, s27
	v_cmp_lt_f32_e32 vcc, 0, v73
	s_waitcnt lgkmcnt(0)
	v_add_f32_e32 v74, v75, v76
	v_mov_b32_e32 v75, v74
	v_cndmask_b32_e32 v82, 0, v65, vcc
	v_ashrrev_i32_e32 v65, 31, v64
	v_mul_f32_e32 v76, v61, v82
	v_lshl_add_u64 v[66:67], v[64:65], 4, s[4:5]
	v_mul_f32_e32 v65, v60, v82
	v_rndne_f32_e32 v76, v76
	v_mul_f32_e32 v77, v62, v82
	v_mul_f32_e32 v78, v63, v82
	v_rndne_f32_e32 v65, v65
	v_cvt_i32_f32_e32 v76, v76
	v_rndne_f32_e32 v77, v77
	v_rndne_f32_e32 v78, v78
	v_cvt_i32_f32_e32 v65, v65
	v_cvt_i32_f32_sdwa v77, v77 dst_sel:WORD_1 dst_unused:UNUSED_PAD src0_sel:DWORD
	v_cvt_i32_f32_e32 v78, v78
	v_lshlrev_b32_e32 v76, 8, v76
	v_and_b32_e32 v76, 0xff00, v76
	v_and_b32_e32 v77, 0xff0000, v77
	v_perm_b32 v65, v78, v65, s28
	v_or3_b32 v76, v65, v76, v77
	v_mul_f32_e32 v77, v57, v82
	v_mul_f32_e32 v65, v56, v82
	v_rndne_f32_e32 v77, v77
	v_mul_f32_e32 v78, v58, v82
	v_mul_f32_e32 v79, v59, v82
	v_rndne_f32_e32 v65, v65
	v_cvt_i32_f32_e32 v77, v77
	v_rndne_f32_e32 v78, v78
	v_rndne_f32_e32 v79, v79
	v_cvt_i32_f32_e32 v65, v65
	v_cvt_i32_f32_sdwa v78, v78 dst_sel:WORD_1 dst_unused:UNUSED_PAD src0_sel:DWORD
	v_cvt_i32_f32_e32 v79, v79
	v_lshlrev_b32_e32 v77, 8, v77
	v_and_b32_e32 v77, 0xff00, v77
	v_and_b32_e32 v78, 0xff0000, v78
	v_perm_b32 v65, v79, v65, s28
	v_or3_b32 v77, v65, v77, v78
	v_mul_f32_e32 v78, v53, v82
	v_mul_f32_e32 v65, v52, v82
	v_rndne_f32_e32 v78, v78
	v_mul_f32_e32 v79, v54, v82
	v_mul_f32_e32 v83, v55, v82
	v_rndne_f32_e32 v65, v65
	v_cvt_i32_f32_e32 v78, v78
	v_rndne_f32_e32 v79, v79
	v_rndne_f32_e32 v83, v83
	v_cvt_i32_f32_e32 v65, v65
	v_cvt_i32_f32_sdwa v79, v79 dst_sel:WORD_1 dst_unused:UNUSED_PAD src0_sel:DWORD
	v_cvt_i32_f32_e32 v83, v83
	v_lshlrev_b32_e32 v78, 8, v78
	v_and_b32_e32 v78, 0xff00, v78
	v_and_b32_e32 v79, 0xff0000, v79
	v_perm_b32 v65, v83, v65, s28
	v_or3_b32 v78, v65, v78, v79
	v_mul_f32_e32 v79, v49, v82
	v_mul_f32_e32 v65, v48, v82
	v_rndne_f32_e32 v79, v79
	v_mul_f32_e32 v83, v50, v82
	v_mul_f32_e32 v84, v51, v82
	v_rndne_f32_e32 v65, v65
	v_cvt_i32_f32_e32 v79, v79
	v_rndne_f32_e32 v83, v83
	v_rndne_f32_e32 v84, v84
	v_cvt_i32_f32_e32 v65, v65
	v_cvt_i32_f32_sdwa v83, v83 dst_sel:WORD_1 dst_unused:UNUSED_PAD src0_sel:DWORD
	v_cvt_i32_f32_e32 v84, v84
	v_lshlrev_b32_e32 v79, 8, v79
	v_and_b32_e32 v79, 0xff00, v79
	v_and_b32_e32 v83, 0xff0000, v83
	v_perm_b32 v65, v84, v65, s28
	v_add_co_u32_e32 v66, vcc, s29, v66
	v_or3_b32 v79, v65, v79, v83
	s_nop 0
	v_addc_co_u32_e32 v67, vcc, 0, v67, vcc
	global_store_dwordx4 v[66:67], v[76:79], off
	v_cvt_pk_bf16_f32 v60, v60, v61
	v_cvt_pk_bf16_f32 v61, v62, v63
	v_cvt_pk_bf16_f32 v62, v56, v57
	v_cvt_pk_bf16_f32 v63, v58, v59
	v_add_co_u32_e32 v58, vcc, s33, v80
	v_permlane32_swap_b32_e32 v74, v75
	s_nop 0
	v_addc_co_u32_e32 v59, vcc, 0, v81, vcc
	v_add_co_u32_e32 v56, vcc, s34, v80
	s_nop 1
	v_addc_co_u32_e32 v57, vcc, 0, v81, vcc
	global_store_dwordx4 v[56:57], v[60:63], off offset:-4096
	v_cvt_pk_bf16_f32 v52, v52, v53
	v_cvt_pk_bf16_f32 v53, v54, v55
	v_cvt_pk_bf16_f32 v54, v48, v49
	v_mul_f32_e32 v49, v33, v82
	v_cvt_pk_bf16_f32 v55, v50, v51
	v_mul_f32_e32 v48, v32, v82
	v_rndne_f32_e32 v49, v49
	v_mul_f32_e32 v50, v34, v82
	v_mul_f32_e32 v51, v35, v82
	v_rndne_f32_e32 v48, v48
	v_cvt_i32_f32_e32 v49, v49
	v_rndne_f32_e32 v50, v50
	v_rndne_f32_e32 v51, v51
	v_cvt_i32_f32_e32 v48, v48
	v_cvt_i32_f32_sdwa v50, v50 dst_sel:WORD_1 dst_unused:UNUSED_PAD src0_sel:DWORD
	v_cvt_i32_f32_e32 v51, v51
	v_lshlrev_b32_e32 v49, 8, v49
	v_and_b32_e32 v49, 0xff00, v49
	v_and_b32_e32 v50, 0xff0000, v50
	v_perm_b32 v48, v51, v48, s28
	v_or3_b32 v48, v48, v49, v50
	v_mul_f32_e32 v50, v45, v82
	global_store_dwordx4 v[58:59], v[52:55], off offset:16
	v_mul_f32_e32 v49, v44, v82
	v_rndne_f32_e32 v50, v50
	v_mul_f32_e32 v51, v46, v82
	v_mul_f32_e32 v52, v47, v82
	v_rndne_f32_e32 v49, v49
	v_cvt_i32_f32_e32 v50, v50
	v_rndne_f32_e32 v51, v51
	v_rndne_f32_e32 v52, v52
	v_cvt_i32_f32_e32 v49, v49
	v_cvt_i32_f32_sdwa v51, v51 dst_sel:WORD_1 dst_unused:UNUSED_PAD src0_sel:DWORD
	v_cvt_i32_f32_e32 v52, v52
	v_lshlrev_b32_e32 v50, 8, v50
	v_and_b32_e32 v50, 0xff00, v50
	v_and_b32_e32 v51, 0xff0000, v51
	v_perm_b32 v49, v52, v49, s28
	v_or3_b32 v49, v49, v50, v51
	v_mul_f32_e32 v51, v41, v82
	v_mul_f32_e32 v50, v40, v82
	v_rndne_f32_e32 v51, v51
	v_mul_f32_e32 v52, v42, v82
	v_mul_f32_e32 v53, v43, v82
	v_rndne_f32_e32 v50, v50
	v_cvt_i32_f32_e32 v51, v51
	v_rndne_f32_e32 v52, v52
	v_rndne_f32_e32 v53, v53
	v_cvt_i32_f32_e32 v50, v50
	v_cvt_i32_f32_sdwa v52, v52 dst_sel:WORD_1 dst_unused:UNUSED_PAD src0_sel:DWORD
	v_cvt_i32_f32_e32 v53, v53
	v_lshlrev_b32_e32 v51, 8, v51
	v_and_b32_e32 v51, 0xff00, v51
	v_and_b32_e32 v52, 0xff0000, v52
	v_perm_b32 v50, v53, v50, s28
	v_or3_b32 v50, v50, v51, v52
	v_mul_f32_e32 v52, v37, v82
	v_mul_f32_e32 v51, v36, v82
	v_rndne_f32_e32 v52, v52
	v_mul_f32_e32 v53, v38, v82
	v_mul_f32_e32 v54, v39, v82
	v_rndne_f32_e32 v51, v51
	v_cvt_i32_f32_e32 v52, v52
	v_rndne_f32_e32 v53, v53
	v_rndne_f32_e32 v54, v54
	v_cvt_i32_f32_e32 v51, v51
	v_cvt_i32_f32_sdwa v53, v53 dst_sel:WORD_1 dst_unused:UNUSED_PAD src0_sel:DWORD
	v_cvt_i32_f32_e32 v54, v54
	v_lshlrev_b32_e32 v52, 8, v52
	v_and_b32_e32 v52, 0xff00, v52
	v_and_b32_e32 v53, 0xff0000, v53
	v_perm_b32 v51, v54, v51, s28
	v_or3_b32 v51, v51, v52, v53
	global_store_dwordx4 v[66:67], v[48:51], off offset:1024
	v_cvt_pk_bf16_f32 v32, v32, v33
	v_cvt_pk_bf16_f32 v33, v34, v35
	v_cvt_pk_bf16_f32 v34, v44, v45
	v_cvt_pk_bf16_f32 v35, v46, v47
	global_store_dwordx4 v[58:59], v[32:35], off offset:2048
	v_cmp_eq_u32_e32 vcc, 0, v64
	s_nop 0
	v_cvt_pk_bf16_f32 v32, v40, v41
	v_cvt_pk_bf16_f32 v33, v42, v43
	v_cvt_pk_bf16_f32 v34, v36, v37
	v_cvt_pk_bf16_f32 v35, v38, v39
	global_store_dwordx4 v[58:59], v[32:35], off offset:2064
	v_mul_f32_e32 v36, v31, v82
	v_rndne_f32_e32 v36, v36
	v_mul_f32_e32 v33, v17, v82
	v_mul_f32_e32 v32, v16, v82
	v_rndne_f32_e32 v33, v33
	v_mul_f32_e32 v34, v18, v82
	v_mul_f32_e32 v35, v19, v82
	v_rndne_f32_e32 v32, v32
	v_cvt_i32_f32_e32 v33, v33
	v_rndne_f32_e32 v34, v34
	v_rndne_f32_e32 v35, v35
	v_cvt_i32_f32_e32 v32, v32
	v_cvt_i32_f32_sdwa v34, v34 dst_sel:WORD_1 dst_unused:UNUSED_PAD src0_sel:DWORD
	v_cvt_i32_f32_e32 v35, v35
	v_lshlrev_b32_e32 v33, 8, v33
	v_and_b32_e32 v33, 0xff00, v33
	v_and_b32_e32 v34, 0xff0000, v34
	v_perm_b32 v32, v35, v32, s28
	v_or3_b32 v32, v32, v33, v34
	v_mul_f32_e32 v34, v29, v82
	v_mul_f32_e32 v33, v28, v82
	v_rndne_f32_e32 v34, v34
	v_mul_f32_e32 v35, v30, v82
	v_rndne_f32_e32 v33, v33
	v_cvt_i32_f32_e32 v34, v34
	v_rndne_f32_e32 v35, v35
	v_cvt_i32_f32_e32 v33, v33
	v_cvt_i32_f32_sdwa v35, v35 dst_sel:WORD_1 dst_unused:UNUSED_PAD src0_sel:DWORD
	v_cvt_i32_f32_e32 v36, v36
	v_lshlrev_b32_e32 v34, 8, v34
	v_and_b32_e32 v34, 0xff00, v34
	v_and_b32_e32 v35, 0xff0000, v35
	v_perm_b32 v33, v36, v33, s28
	v_or3_b32 v33, v33, v34, v35
	v_mul_f32_e32 v35, v25, v82
	v_mul_f32_e32 v34, v24, v82
	v_rndne_f32_e32 v35, v35
	v_mul_f32_e32 v36, v26, v82
	v_mul_f32_e32 v37, v27, v82
	v_rndne_f32_e32 v34, v34
	v_cvt_i32_f32_e32 v35, v35
	v_rndne_f32_e32 v36, v36
	v_rndne_f32_e32 v37, v37
	v_cvt_i32_f32_e32 v34, v34
	v_cvt_i32_f32_sdwa v36, v36 dst_sel:WORD_1 dst_unused:UNUSED_PAD src0_sel:DWORD
	v_cvt_i32_f32_e32 v37, v37
	v_lshlrev_b32_e32 v35, 8, v35
	v_and_b32_e32 v35, 0xff00, v35
	v_and_b32_e32 v36, 0xff0000, v36
	v_perm_b32 v34, v37, v34, s28
	v_or3_b32 v34, v34, v35, v36
	v_mul_f32_e32 v36, v21, v82
	v_mul_f32_e32 v35, v20, v82
	v_rndne_f32_e32 v36, v36
	v_mul_f32_e32 v37, v22, v82
	v_mul_f32_e32 v38, v23, v82
	v_rndne_f32_e32 v35, v35
	v_cvt_i32_f32_e32 v36, v36
	v_rndne_f32_e32 v37, v37
	v_rndne_f32_e32 v38, v38
	v_cvt_i32_f32_e32 v35, v35
	v_cvt_i32_f32_sdwa v37, v37 dst_sel:WORD_1 dst_unused:UNUSED_PAD src0_sel:DWORD
	v_cvt_i32_f32_e32 v38, v38
	v_lshlrev_b32_e32 v36, 8, v36
	v_and_b32_e32 v36, 0xff00, v36
	v_and_b32_e32 v37, 0xff0000, v37
	v_perm_b32 v35, v38, v35, s28
	v_or3_b32 v35, v35, v36, v37
	global_store_dwordx4 v[66:67], v[32:35], off offset:2048
	v_cvt_pk_bf16_f32 v16, v16, v17
	v_cvt_pk_bf16_f32 v17, v18, v19
	v_cvt_pk_bf16_f32 v18, v28, v29
	v_cvt_pk_bf16_f32 v19, v30, v31
	global_store_dwordx4 v[56:57], v[16:19], off
	s_nop 1
	v_cvt_pk_bf16_f32 v16, v24, v25
	v_cvt_pk_bf16_f32 v17, v26, v27
	v_cvt_pk_bf16_f32 v18, v20, v21
	v_cvt_pk_bf16_f32 v19, v22, v23
	global_store_dwordx4 v[56:57], v[16:19], off offset:16
	v_mul_f32_e32 v20, v15, v82
	v_rndne_f32_e32 v20, v20
	v_mul_f32_e32 v17, v1, v82
	v_mul_f32_e32 v16, v0, v82
	v_rndne_f32_e32 v17, v17
	v_mul_f32_e32 v18, v2, v82
	v_mul_f32_e32 v19, v3, v82
	v_rndne_f32_e32 v16, v16
	v_cvt_i32_f32_e32 v17, v17
	v_rndne_f32_e32 v18, v18
	v_rndne_f32_e32 v19, v19
	v_cvt_i32_f32_e32 v16, v16
	v_cvt_i32_f32_sdwa v18, v18 dst_sel:WORD_1 dst_unused:UNUSED_PAD src0_sel:DWORD
	v_cvt_i32_f32_e32 v19, v19
	v_lshlrev_b32_e32 v17, 8, v17
	v_and_b32_e32 v17, 0xff00, v17
	v_and_b32_e32 v18, 0xff0000, v18
	v_perm_b32 v16, v19, v16, s28
	v_or3_b32 v16, v16, v17, v18
	v_mul_f32_e32 v18, v13, v82
	v_mul_f32_e32 v17, v12, v82
	v_rndne_f32_e32 v18, v18
	v_mul_f32_e32 v19, v14, v82
	v_rndne_f32_e32 v17, v17
	v_cvt_i32_f32_e32 v18, v18
	v_rndne_f32_e32 v19, v19
	v_cvt_i32_f32_e32 v17, v17
	v_cvt_i32_f32_sdwa v19, v19 dst_sel:WORD_1 dst_unused:UNUSED_PAD src0_sel:DWORD
	v_cvt_i32_f32_e32 v20, v20
	v_lshlrev_b32_e32 v18, 8, v18
	v_and_b32_e32 v18, 0xff00, v18
	v_and_b32_e32 v19, 0xff0000, v19
	v_perm_b32 v17, v20, v17, s28
	v_or3_b32 v17, v17, v18, v19
	v_mul_f32_e32 v19, v9, v82
	v_mul_f32_e32 v18, v8, v82
	v_rndne_f32_e32 v19, v19
	v_mul_f32_e32 v20, v10, v82
	v_mul_f32_e32 v21, v11, v82
	v_rndne_f32_e32 v18, v18
	v_cvt_i32_f32_e32 v19, v19
	v_rndne_f32_e32 v20, v20
	v_rndne_f32_e32 v21, v21
	v_cvt_i32_f32_e32 v18, v18
	v_cvt_i32_f32_sdwa v20, v20 dst_sel:WORD_1 dst_unused:UNUSED_PAD src0_sel:DWORD
	v_cvt_i32_f32_e32 v21, v21
	v_lshlrev_b32_e32 v19, 8, v19
	v_and_b32_e32 v19, 0xff00, v19
	v_and_b32_e32 v20, 0xff0000, v20
	v_perm_b32 v18, v21, v18, s28
	v_or3_b32 v18, v18, v19, v20
	v_mul_f32_e32 v20, v5, v82
	v_mul_f32_e32 v19, v4, v82
	v_rndne_f32_e32 v20, v20
	v_mul_f32_e32 v21, v6, v82
	v_mul_f32_e32 v22, v7, v82
	v_rndne_f32_e32 v19, v19
	v_cvt_i32_f32_e32 v20, v20
	v_rndne_f32_e32 v21, v21
	v_rndne_f32_e32 v22, v22
	v_cvt_i32_f32_e32 v19, v19
	v_cvt_i32_f32_sdwa v21, v21 dst_sel:WORD_1 dst_unused:UNUSED_PAD src0_sel:DWORD
	v_cvt_i32_f32_e32 v22, v22
	v_lshlrev_b32_e32 v20, 8, v20
	v_and_b32_e32 v20, 0xff00, v20
	v_and_b32_e32 v21, 0xff0000, v21
	v_perm_b32 v19, v22, v19, s28
	v_or3_b32 v19, v19, v20, v21
	global_store_dwordx4 v[66:67], v[16:19], off offset:3072
	v_cvt_pk_bf16_f32 v0, v0, v1
	v_cvt_pk_bf16_f32 v1, v2, v3
	v_cvt_pk_bf16_f32 v2, v12, v13
	v_cvt_pk_bf16_f32 v3, v14, v15
	global_store_dwordx4 v[56:57], v[0:3], off offset:2048
	s_nop 1
	v_cvt_pk_bf16_f32 v0, v8, v9
	v_cvt_pk_bf16_f32 v1, v10, v11
	v_cvt_pk_bf16_f32 v2, v4, v5
	v_cvt_pk_bf16_f32 v3, v6, v7
	global_store_dwordx4 v[56:57], v[0:3], off offset:2064
	s_and_saveexec_b64 s[30:31], vcc
	s_cbranch_execz .LBB0_98
	v_add_f32_e32 v0, v74, v75
	v_fmamk_f32 v0, v0, 0x39800000, v69
	v_mul_f32_e32 v1, 0x4f800000, v0
	v_cmp_gt_f32_e32 vcc, s35, v0
	s_nop 1
	v_cndmask_b32_e32 v0, v0, v1, vcc
	v_sqrt_f32_e32 v1, v0
	s_nop 0
	v_add_u32_e32 v2, -1, v1
	v_fma_f32 v4, -v2, v1, v0
	v_add_u32_e32 v3, 1, v1
	v_cmp_ge_f32_e64 s[4:5], 0, v4
	s_nop 1
	v_cndmask_b32_e64 v2, v1, v2, s[4:5]
	v_fma_f32 v1, -v3, v1, v0
	v_cmp_lt_f32_e64 s[4:5], 0, v1
	s_nop 1
	v_cndmask_b32_e64 v1, v2, v3, s[4:5]
	v_mul_f32_e32 v2, 0x37800000, v1
	v_cndmask_b32_e32 v1, v1, v2, vcc
	v_cmp_class_f32_e32 vcc, v0, v70
	s_nop 1
	v_cndmask_b32_e32 v0, v1, v0, vcc
	v_div_scale_f32 v1, s[4:5], v0, v0, 1.0
	v_rcp_f32_e32 v2, v1
	s_add_u32 s4, s16, s6
	s_addc_u32 s5, s17, s7
	v_fma_f32 v3, -v1, v2, 1.0
	v_fmac_f32_e32 v2, v3, v2
	v_div_scale_f32 v3, vcc, 1.0, v0, 1.0
	v_mul_f32_e32 v4, v3, v2
	v_fma_f32 v5, -v1, v4, v3
	v_fmac_f32_e32 v4, v5, v2
	v_fma_f32 v1, -v1, v4, v3
	v_div_fmas_f32 v1, v1, v2, v4
	v_div_fixup_f32 v0, v1, v0, 1.0
	global_store_dword v71, v0, s[4:5]
	v_mul_f32_e32 v0, v73, v0
	v_mul_f32_e32 v0, 0x3c010204, v0
	global_store_dword v72, v0, s[4:5]
	s_branch .LBB0_98
.LBB0_101:
	s_nop 0
	s_nop 0
	s_nop 0
	s_nop 0
	s_nop 0
	s_nop 0
	s_nop 0
	s_nop 0
	s_nop 0
	s_nop 0
	s_nop 0
	s_nop 0
	s_mov_b32 s0, -1
	s_waitcnt vmcnt(0)
	s_barrier
	s_nop 0
	v_mbcnt_lo_u32_b32 v0, s0, 0
	v_mbcnt_hi_u32_b32 v0, s0, v0
	v_add_u32_e32 v0, s76, v0
	s_nop 0
	v_cmp_eq_u32_e32 vcc, 0, v0
	s_and_saveexec_b64 s[4:5], vcc
	s_cbranch_execz .LBB0_153
	s_add_i32 s1, 0, 0x22160
	v_mov_b32_e32 v0, s1
	s_getreg_b32 s0, hwreg(HW_REG_XCC_ID, 0, 4)
	s_waitcnt vmcnt(0) expcnt(0) lgkmcnt(0)
	ds_read_b32 v2, v0
	s_add_i32 s1, 0, 0x22164
	v_mov_b32_e32 v0, s1
	ds_read_b32 v0, v0
	s_and_b32 s3, s0, 15
	s_waitcnt lgkmcnt(1)
	v_cmp_ne_u32_e32 vcc, 0, v2
	s_cbranch_vccnz .LBB0_117
	s_add_u32 s6, s12, 0x4200
	s_addc_u32 s7, s13, 0
	s_add_u32 s8, s12, 0x4400
	s_addc_u32 s9, s13, 0
	s_add_u32 s10, s12, 0x4500
	s_addc_u32 s11, s13, 0
	s_add_u32 s16, s12, 0x4600
	s_addc_u32 s17, s13, 0
	s_add_u32 s18, s12, 0x4700
	s_addc_u32 s19, s13, 0
	s_add_u32 s20, s12, 0x4800
	s_addc_u32 s21, s13, 0
	s_add_u32 s22, s12, 0x4900
	s_addc_u32 s23, s13, 0
	s_add_u32 s30, s12, 0x4a00
	s_addc_u32 s31, s13, 0
	s_add_u32 s34, s12, 0x4b00
	s_addc_u32 s35, s13, 0
	s_add_u32 s36, s12, 0x4c00
	s_addc_u32 s37, s13, 0
	s_add_u32 s38, s12, 0x4d00
	s_addc_u32 s39, s13, 0
	s_add_u32 s40, s12, 0x4e00
	s_addc_u32 s41, s13, 0
	s_add_u32 s42, s12, 0x4f00
	s_addc_u32 s43, s13, 0
	s_add_u32 s44, s12, 0x5000
	s_addc_u32 s45, s13, 0
	s_add_u32 s46, s12, 0x5100
	s_addc_u32 s47, s13, 0
	s_add_u32 s48, s12, 0x5200
	s_addc_u32 s49, s13, 0
	s_add_u32 s50, s12, 0x5300
	s_addc_u32 s51, s13, 0
	s_mov_b32 s0, 1
	v_mov_b32_e32 v16, 0
	s_movk_i32 s1, 0x100
	s_branch .LBB0_105

.LBB0_162:
	s_waitcnt vmcnt(6)
	v_and_b32_e32 v91, 0xffff0000, v6
	v_lshlrev_b32_e32 v90, 16, v6
	v_mul_f32_e32 v87, v91, v91
	v_lshlrev_b32_e32 v92, 16, v7
	v_fmac_f32_e32 v87, v90, v90
	v_and_b32_e32 v93, 0xffff0000, v7
	v_fmac_f32_e32 v87, v92, v92
	v_lshlrev_b32_e32 v94, 16, v8
	v_fmac_f32_e32 v87, v93, v93
	v_and_b32_e32 v95, 0xffff0000, v8
	v_fmac_f32_e32 v87, v94, v94
	v_lshlrev_b32_e32 v96, 16, v9
	v_fmac_f32_e32 v87, v95, v95
	v_and_b32_e32 v97, 0xffff0000, v9
	v_fmac_f32_e32 v87, v96, v96
	v_lshlrev_b32_e32 v98, 16, v2
	v_fmac_f32_e32 v87, v97, v97
	v_and_b32_e32 v99, 0xffff0000, v2
	v_fmac_f32_e32 v87, v98, v98
	v_lshlrev_b32_e32 v100, 16, v3
	v_fmac_f32_e32 v87, v99, v99
	v_and_b32_e32 v101, 0xffff0000, v3
	v_fmac_f32_e32 v87, v100, v100
	v_lshlrev_b32_e32 v102, 16, v4
	v_fmac_f32_e32 v87, v101, v101
	v_and_b32_e32 v103, 0xffff0000, v4
	v_fmac_f32_e32 v87, v102, v102
	v_lshlrev_b32_e32 v104, 16, v5
	v_fmac_f32_e32 v87, v103, v103
	v_and_b32_e32 v105, 0xffff0000, v5
	v_fmac_f32_e32 v87, v104, v104
	s_waitcnt vmcnt(4)
	v_lshlrev_b32_e32 v106, 16, v14
	v_fmac_f32_e32 v87, v105, v105
	v_and_b32_e32 v107, 0xffff0000, v14
	v_fmac_f32_e32 v87, v106, v106
	v_lshlrev_b32_e32 v108, 16, v15
	v_fmac_f32_e32 v87, v107, v107
	v_and_b32_e32 v109, 0xffff0000, v15
	v_fmac_f32_e32 v87, v108, v108
	v_lshlrev_b32_e32 v110, 16, v16
	v_fmac_f32_e32 v87, v109, v109
	v_and_b32_e32 v111, 0xffff0000, v16
	v_fmac_f32_e32 v87, v110, v110
	v_lshlrev_b32_e32 v112, 16, v17
	v_fmac_f32_e32 v87, v111, v111
	v_and_b32_e32 v113, 0xffff0000, v17
	v_fmac_f32_e32 v87, v112, v112
	v_max3_f32 v0, |v90|, 0, |v91|
	v_lshlrev_b32_e32 v114, 16, v10
	v_fmac_f32_e32 v87, v113, v113
	v_max3_f32 v0, v0, |v92|, |v93|
	v_and_b32_e32 v115, 0xffff0000, v10
	v_fmac_f32_e32 v87, v114, v114
	v_max3_f32 v0, v0, |v94|, |v95|
	v_lshlrev_b32_e32 v116, 16, v11
	v_fmac_f32_e32 v87, v115, v115
	v_max3_f32 v0, v0, |v96|, |v97|
	v_and_b32_e32 v117, 0xffff0000, v11
	v_fmac_f32_e32 v87, v116, v116
	v_max3_f32 v0, v0, |v98|, |v99|
	v_lshlrev_b32_e32 v118, 16, v12
	v_fmac_f32_e32 v87, v117, v117
	v_max3_f32 v0, v0, |v100|, |v101|
	v_and_b32_e32 v119, 0xffff0000, v12
	v_fmac_f32_e32 v87, v118, v118
	v_max3_f32 v0, v0, |v102|, |v103|
	v_lshlrev_b32_e32 v120, 16, v13
	v_fmac_f32_e32 v87, v119, v119
	v_max3_f32 v0, v0, |v104|, |v105|
	v_and_b32_e32 v121, 0xffff0000, v13
	v_fmac_f32_e32 v87, v120, v120
	v_max3_f32 v0, v0, |v106|, |v107|
	s_waitcnt vmcnt(3)
	v_lshlrev_b32_e32 v122, 16, v18
	v_fmac_f32_e32 v87, v121, v121
	v_max3_f32 v0, v0, |v108|, |v109|
	v_and_b32_e32 v123, 0xffff0000, v18
	v_fmac_f32_e32 v87, v122, v122
	v_max3_f32 v0, v0, |v110|, |v111|
	v_lshlrev_b32_e32 v124, 16, v19
	v_fmac_f32_e32 v87, v123, v123
	v_max3_f32 v0, v0, |v112|, |v113|
	v_and_b32_e32 v125, 0xffff0000, v19
	v_fmac_f32_e32 v87, v124, v124
	v_max3_f32 v0, v0, |v114|, |v115|
	v_lshlrev_b32_e32 v126, 16, v20
	v_fmac_f32_e32 v87, v125, v125
	v_max3_f32 v0, v0, |v116|, |v117|
	v_and_b32_e32 v127, 0xffff0000, v20
	v_fmac_f32_e32 v87, v126, v126
	v_max3_f32 v0, v0, |v118|, |v119|
	v_lshlrev_b32_e32 v128, 16, v21
	v_fmac_f32_e32 v87, v127, v127
	v_max3_f32 v0, v0, |v120|, |v121|
	v_and_b32_e32 v129, 0xffff0000, v21
	v_fmac_f32_e32 v87, v128, v128
	s_waitcnt vmcnt(2)
	v_lshlrev_b32_e32 v130, 16, v22
	v_max3_f32 v0, v0, |v122|, |v123|
	v_fmac_f32_e32 v87, v129, v129
	v_and_b32_e32 v131, 0xffff0000, v22
	v_max3_f32 v0, v0, |v124|, |v125|
	v_fmac_f32_e32 v87, v130, v130
	v_lshlrev_b32_e32 v132, 16, v23
	v_max3_f32 v0, v0, |v126|, |v127|
	v_fmac_f32_e32 v87, v131, v131
	v_and_b32_e32 v133, 0xffff0000, v23
	v_max3_f32 v0, v0, |v128|, |v129|
	v_fmac_f32_e32 v87, v132, v132
	v_lshlrev_b32_e32 v134, 16, v24
	v_max3_f32 v0, v0, |v130|, |v131|
	v_fmac_f32_e32 v87, v133, v133
	v_and_b32_e32 v135, 0xffff0000, v24
	v_max3_f32 v0, v0, |v132|, |v133|
	v_fmac_f32_e32 v87, v134, v134
	v_lshlrev_b32_e32 v136, 16, v25
	v_and_b32_e32 v137, 0xffff0000, v25
	v_max3_f32 v0, v0, |v134|, |v135|
	v_fmac_f32_e32 v87, v135, v135
	v_max3_f32 v80, v0, |v136|, |v137|
	s_waitcnt vmcnt(1)
	v_lshlrev_b32_e32 v138, 16, v26
	v_and_b32_e32 v139, 0xffff0000, v26
	v_fmac_f32_e32 v87, v136, v136
	v_lshlrev_b32_e32 v140, 16, v27
	v_and_b32_e32 v141, 0xffff0000, v27
	v_max3_f32 v80, v80, |v138|, |v139|
	v_fmac_f32_e32 v87, v137, v137
	v_lshlrev_b32_e32 v142, 16, v28
	v_and_b32_e32 v143, 0xffff0000, v28
	v_max3_f32 v80, v80, |v140|, |v141|
	v_fmac_f32_e32 v87, v138, v138
	v_lshlrev_b32_e32 v144, 16, v29
	v_and_b32_e32 v145, 0xffff0000, v29
	v_max3_f32 v80, v80, |v142|, |v143|
	v_fmac_f32_e32 v87, v139, v139
	s_waitcnt vmcnt(0)
	v_lshlrev_b32_e32 v146, 16, v30
	v_and_b32_e32 v86, 0xffff0000, v30
	v_max3_f32 v80, v80, |v144|, |v145|
	v_fmac_f32_e32 v87, v140, v140
	v_lshlrev_b32_e32 v85, 16, v31
	v_and_b32_e32 v84, 0xffff0000, v31
	v_max3_f32 v80, v80, |v146|, |v86|
	v_fmac_f32_e32 v87, v141, v141
	v_lshlrev_b32_e32 v83, 16, v32
	v_and_b32_e32 v82, 0xffff0000, v32
	v_max3_f32 v80, v80, |v85|, |v84|
	v_fmac_f32_e32 v87, v142, v142
	v_lshlrev_b32_e32 v35, 16, v33
	v_and_b32_e32 v0, 0xffff0000, v33
	v_max3_f32 v80, v80, |v83|, |v82|
	v_fmac_f32_e32 v87, v143, v143
	v_max3_f32 v80, v80, |v35|, |v0|
	v_fmac_f32_e32 v87, v144, v144
	s_nop 1
	v_mov_b32_dpp v81, v80 quad_perm:[1,0,3,2] row_mask:0xf bank_mask:0xf
	v_fmac_f32_e32 v87, v145, v145
	v_fmac_f32_e32 v87, v146, v146
	v_fmac_f32_e32 v87, v86, v86
	v_fmac_f32_e32 v87, v85, v85
	v_fmac_f32_e32 v87, v84, v84
	s_waitcnt lgkmcnt(0)
	v_max_f32_e32 v81, v81, v81
	v_fmac_f32_e32 v87, v83, v83
	v_max_f32_e32 v80, v80, v81
	v_fmac_f32_e32 v87, v82, v82
	s_nop 1
	v_mov_b32_dpp v81, v80 quad_perm:[2,3,0,1] row_mask:0xf bank_mask:0xf
	v_fmac_f32_e32 v87, v35, v35
	v_fmac_f32_e32 v87, v0, v0
	s_nop 1
	v_mov_b32_dpp v88, v87 quad_perm:[1,0,3,2] row_mask:0xf bank_mask:0xf
	s_waitcnt lgkmcnt(0)
	v_max_f32_e32 v81, v81, v81
	v_max_f32_e32 v80, v80, v81
	s_nop 1
	v_mov_b32_dpp v81, v80 row_shl:4 row_mask:0xf bank_mask:0x5
	v_mov_b32_dpp v81, v80 row_shr:4 row_mask:0xf bank_mask:0xa
	s_waitcnt lgkmcnt(0)
	v_add_f32_e32 v87, v87, v88
	s_nop 1
	v_mov_b32_dpp v88, v87 quad_perm:[2,3,0,1] row_mask:0xf bank_mask:0xf
	s_waitcnt lgkmcnt(0)
	v_max_f32_e32 v81, v81, v81
	v_max_f32_e32 v80, v80, v81
	s_waitcnt lgkmcnt(0)
	v_add_f32_e32 v87, v87, v88
	s_nop 1
	v_mov_b32_dpp v81, v80 row_ror:8 row_mask:0xf bank_mask:0xf
	s_nop 1
	v_mov_b32_dpp v88, v87 row_shl:4 row_mask:0xf bank_mask:0x5
	v_mov_b32_dpp v88, v87 row_shr:4 row_mask:0xf bank_mask:0xa
	s_waitcnt lgkmcnt(0)
	v_max_f32_e32 v81, v81, v81
	s_waitcnt lgkmcnt(0)
	v_add_f32_e32 v87, v87, v88
	v_max_f32_e32 v80, v80, v81
	s_nop 1
	v_mov_b32_dpp v88, v87 row_ror:8 row_mask:0xf bank_mask:0xf
	ds_swizzle_b32 v81, v80 offset:swizzle(SWAP,16)
	s_waitcnt lgkmcnt(0)
	v_add_f32_e32 v87, v87, v88
	s_waitcnt lgkmcnt(0)
	v_max_f32_e32 v81, v81, v81
	ds_swizzle_b32 v88, v87 offset:swizzle(SWAP,16)
	v_max_f32_e32 v80, v80, v81
	v_mov_b32_e32 v81, v80
	s_nop 1
	v_permlane32_swap_b32_e32 v80, v81
	v_max_f32_e32 v81, v81, v81
	v_max_f32_e32 v80, v80, v80
	s_waitcnt lgkmcnt(0)
	v_add_f32_e32 v88, v87, v88
	v_max_f32_e32 v87, v80, v81
	v_div_scale_f32 v80, s[6:7], v87, v87, s79
	v_rcp_f32_e32 v81, v80
	v_mov_b32_e32 v89, v88
	s_nop 1
	v_permlane32_swap_b32_e32 v88, v89
	v_fma_f32 v147, -v80, v81, 1.0
	v_fmac_f32_e32 v81, v147, v81
	v_div_scale_f32 v147, vcc, s79, v87, s79
	v_mul_f32_e32 v148, v147, v81
	v_fma_f32 v149, -v80, v148, v147
	v_fmac_f32_e32 v148, v149, v81
	v_fma_f32 v80, -v80, v148, v147
	v_div_fmas_f32 v80, v80, v81, v148
	v_div_fixup_f32 v80, v80, v87, s79
	v_cmp_lt_f32_e32 vcc, 0, v87
	s_nop 1
	v_cndmask_b32_e32 v147, 0, v80, vcc
	v_mul_f32_e32 v91, v147, v91
	v_mul_f32_e32 v90, v147, v90
	v_rndne_f32_e32 v91, v91
	v_mul_f32_e32 v92, v147, v92
	v_mul_f32_e32 v93, v147, v93
	v_rndne_f32_e32 v90, v90
	v_cvt_i32_f32_e32 v91, v91
	v_rndne_f32_e32 v92, v92
	v_rndne_f32_e32 v93, v93
	v_cvt_i32_f32_e32 v90, v90
	v_cvt_i32_f32_sdwa v92, v92 dst_sel:WORD_1 dst_unused:UNUSED_PAD src0_sel:DWORD
	v_cvt_i32_f32_e32 v93, v93
	v_lshlrev_b32_e32 v91, 8, v91
	v_and_b32_e32 v91, 0xff00, v91
	v_and_b32_e32 v92, 0xff0000, v92
	v_perm_b32 v90, v93, v90, s81
	v_or3_b32 v90, v90, v91, v92
	v_mul_f32_e32 v92, v147, v95
	v_mul_f32_e32 v91, v147, v94
	v_rndne_f32_e32 v92, v92
	v_mul_f32_e32 v93, v147, v96
	v_mul_f32_e32 v94, v147, v97
	v_rndne_f32_e32 v91, v91
	v_cvt_i32_f32_e32 v92, v92
	v_rndne_f32_e32 v93, v93
	v_rndne_f32_e32 v94, v94
	v_cvt_i32_f32_e32 v91, v91
	v_cvt_i32_f32_sdwa v93, v93 dst_sel:WORD_1 dst_unused:UNUSED_PAD src0_sel:DWORD
	v_cvt_i32_f32_e32 v94, v94
	v_lshlrev_b32_e32 v92, 8, v92
	v_and_b32_e32 v92, 0xff00, v92
	v_and_b32_e32 v93, 0xff0000, v93
	v_perm_b32 v91, v94, v91, s81
	v_or3_b32 v91, v91, v92, v93
	v_mul_f32_e32 v93, v147, v99
	v_mul_f32_e32 v92, v147, v98
	v_rndne_f32_e32 v93, v93
	v_mul_f32_e32 v94, v147, v100
	v_mul_f32_e32 v95, v147, v101
	v_rndne_f32_e32 v92, v92
	v_cvt_i32_f32_e32 v93, v93
	v_rndne_f32_e32 v94, v94
	v_rndne_f32_e32 v95, v95
	v_cvt_i32_f32_e32 v92, v92
	v_cvt_i32_f32_sdwa v94, v94 dst_sel:WORD_1 dst_unused:UNUSED_PAD src0_sel:DWORD
	v_cvt_i32_f32_e32 v95, v95
	v_lshlrev_b32_e32 v93, 8, v93
	v_and_b32_e32 v93, 0xff00, v93
	v_and_b32_e32 v94, 0xff0000, v94
	v_perm_b32 v92, v95, v92, s81
	v_or3_b32 v92, v92, v93, v94
	v_mul_f32_e32 v94, v147, v103
	v_mul_f32_e32 v93, v147, v102
	v_rndne_f32_e32 v94, v94
	v_mul_f32_e32 v95, v147, v104
	v_mul_f32_e32 v96, v147, v105
	v_rndne_f32_e32 v93, v93
	v_cvt_i32_f32_e32 v94, v94
	v_rndne_f32_e32 v95, v95
	v_rndne_f32_e32 v96, v96
	v_cvt_i32_f32_e32 v93, v93
	v_cvt_i32_f32_sdwa v95, v95 dst_sel:WORD_1 dst_unused:UNUSED_PAD src0_sel:DWORD
	v_cvt_i32_f32_e32 v96, v96
	v_lshl_add_u64 v[80:81], s[8:9], 0, v[70:71]
	v_lshlrev_b32_e32 v94, 8, v94
	v_and_b32_e32 v94, 0xff00, v94
	v_and_b32_e32 v95, 0xff0000, v95
	v_perm_b32 v93, v96, v93, s81
	v_add_co_u32_e32 v80, vcc, s20, v80
	v_or3_b32 v93, v93, v94, v95
	s_nop 0
	v_addc_co_u32_e32 v81, vcc, 0, v81, vcc
	global_store_dwordx4 v[80:81], v[90:93], off
	v_mul_f32_e32 v94, v147, v113
	v_rndne_f32_e32 v94, v94
	v_mul_f32_e32 v91, v147, v107
	v_mul_f32_e32 v90, v147, v106
	v_rndne_f32_e32 v91, v91
	v_mul_f32_e32 v92, v147, v108
	v_mul_f32_e32 v93, v147, v109
	v_rndne_f32_e32 v90, v90
	v_cvt_i32_f32_e32 v91, v91
	v_rndne_f32_e32 v92, v92
	v_rndne_f32_e32 v93, v93
	v_cvt_i32_f32_e32 v90, v90
	v_cvt_i32_f32_sdwa v92, v92 dst_sel:WORD_1 dst_unused:UNUSED_PAD src0_sel:DWORD
	v_cvt_i32_f32_e32 v93, v93
	v_lshlrev_b32_e32 v91, 8, v91
	v_and_b32_e32 v91, 0xff00, v91
	v_and_b32_e32 v92, 0xff0000, v92
	v_perm_b32 v90, v93, v90, s81
	v_or3_b32 v90, v90, v91, v92
	v_mul_f32_e32 v92, v147, v111
	v_mul_f32_e32 v91, v147, v110
	v_rndne_f32_e32 v92, v92
	v_mul_f32_e32 v93, v147, v112
	v_rndne_f32_e32 v91, v91
	v_cvt_i32_f32_e32 v92, v92
	v_rndne_f32_e32 v93, v93
	v_cvt_i32_f32_e32 v91, v91
	v_cvt_i32_f32_sdwa v93, v93 dst_sel:WORD_1 dst_unused:UNUSED_PAD src0_sel:DWORD
	v_cvt_i32_f32_e32 v94, v94
	v_lshlrev_b32_e32 v92, 8, v92
	v_and_b32_e32 v92, 0xff00, v92
	v_and_b32_e32 v93, 0xff0000, v93
	v_perm_b32 v91, v94, v91, s81
	v_or3_b32 v91, v91, v92, v93
	v_mul_f32_e32 v93, v147, v115
	v_mul_f32_e32 v92, v147, v114
	v_rndne_f32_e32 v93, v93
	v_mul_f32_e32 v94, v147, v116
	v_mul_f32_e32 v95, v147, v117
	v_rndne_f32_e32 v92, v92
	v_cvt_i32_f32_e32 v93, v93
	v_rndne_f32_e32 v94, v94
	v_rndne_f32_e32 v95, v95
	v_cvt_i32_f32_e32 v92, v92
	v_cvt_i32_f32_sdwa v94, v94 dst_sel:WORD_1 dst_unused:UNUSED_PAD src0_sel:DWORD
	v_cvt_i32_f32_e32 v95, v95
	v_lshlrev_b32_e32 v93, 8, v93
	v_and_b32_e32 v93, 0xff00, v93
	v_and_b32_e32 v94, 0xff0000, v94
	v_perm_b32 v92, v95, v92, s81
	v_or3_b32 v92, v92, v93, v94
	v_mul_f32_e32 v94, v147, v119
	v_mul_f32_e32 v93, v147, v118
	v_rndne_f32_e32 v94, v94
	v_mul_f32_e32 v95, v147, v120
	v_mul_f32_e32 v96, v147, v121
	v_rndne_f32_e32 v93, v93
	v_cvt_i32_f32_e32 v94, v94
	v_rndne_f32_e32 v95, v95
	v_rndne_f32_e32 v96, v96
	v_cvt_i32_f32_e32 v93, v93
	v_cvt_i32_f32_sdwa v95, v95 dst_sel:WORD_1 dst_unused:UNUSED_PAD src0_sel:DWORD
	v_cvt_i32_f32_e32 v96, v96
	v_lshlrev_b32_e32 v94, 8, v94
	v_and_b32_e32 v94, 0xff00, v94
	v_and_b32_e32 v95, 0xff0000, v95
	v_perm_b32 v93, v96, v93, s81
	v_or3_b32 v93, v93, v94, v95
	global_store_dwordx4 v[80:81], v[90:93], off offset:1024
	v_mul_f32_e32 v94, v147, v129
	v_rndne_f32_e32 v94, v94
	v_mul_f32_e32 v91, v147, v123
	v_mul_f32_e32 v90, v147, v122
	v_rndne_f32_e32 v91, v91
	v_mul_f32_e32 v92, v147, v124
	v_mul_f32_e32 v93, v147, v125
	v_rndne_f32_e32 v90, v90
	v_cvt_i32_f32_e32 v91, v91
	v_rndne_f32_e32 v92, v92
	v_rndne_f32_e32 v93, v93
	v_cvt_i32_f32_e32 v90, v90
	v_cvt_i32_f32_sdwa v92, v92 dst_sel:WORD_1 dst_unused:UNUSED_PAD src0_sel:DWORD
	v_cvt_i32_f32_e32 v93, v93
	v_lshlrev_b32_e32 v91, 8, v91
	v_and_b32_e32 v91, 0xff00, v91
	v_and_b32_e32 v92, 0xff0000, v92
	v_perm_b32 v90, v93, v90, s81
	v_or3_b32 v90, v90, v91, v92
	v_mul_f32_e32 v92, v147, v127
	v_mul_f32_e32 v91, v147, v126
	v_rndne_f32_e32 v92, v92
	v_mul_f32_e32 v93, v147, v128
	v_rndne_f32_e32 v91, v91
	v_cvt_i32_f32_e32 v92, v92
	v_rndne_f32_e32 v93, v93
	v_cvt_i32_f32_e32 v91, v91
	v_cvt_i32_f32_sdwa v93, v93 dst_sel:WORD_1 dst_unused:UNUSED_PAD src0_sel:DWORD
	v_cvt_i32_f32_e32 v94, v94
	v_lshlrev_b32_e32 v92, 8, v92
	v_and_b32_e32 v92, 0xff00, v92
	v_and_b32_e32 v93, 0xff0000, v93
	v_perm_b32 v91, v94, v91, s81
	v_or3_b32 v91, v91, v92, v93
	v_mul_f32_e32 v93, v147, v131
	v_mul_f32_e32 v92, v147, v130
	v_rndne_f32_e32 v93, v93
	v_mul_f32_e32 v94, v147, v132
	v_mul_f32_e32 v95, v147, v133
	v_rndne_f32_e32 v92, v92
	v_cvt_i32_f32_e32 v93, v93
	v_rndne_f32_e32 v94, v94
	v_rndne_f32_e32 v95, v95
	v_cvt_i32_f32_e32 v92, v92
	v_cvt_i32_f32_sdwa v94, v94 dst_sel:WORD_1 dst_unused:UNUSED_PAD src0_sel:DWORD
	v_cvt_i32_f32_e32 v95, v95
	v_lshlrev_b32_e32 v93, 8, v93
	v_and_b32_e32 v93, 0xff00, v93
	v_and_b32_e32 v94, 0xff0000, v94
	v_perm_b32 v92, v95, v92, s81
	v_or3_b32 v92, v92, v93, v94
	v_mul_f32_e32 v94, v147, v135
	v_mul_f32_e32 v93, v147, v134
	v_rndne_f32_e32 v94, v94
	v_mul_f32_e32 v95, v147, v136
	v_mul_f32_e32 v96, v147, v137
	v_rndne_f32_e32 v93, v93
	v_cvt_i32_f32_e32 v94, v94
	v_rndne_f32_e32 v95, v95
	v_rndne_f32_e32 v96, v96
	v_cvt_i32_f32_e32 v93, v93
	v_cvt_i32_f32_sdwa v95, v95 dst_sel:WORD_1 dst_unused:UNUSED_PAD src0_sel:DWORD
	v_cvt_i32_f32_e32 v96, v96
	v_lshlrev_b32_e32 v94, 8, v94
	v_and_b32_e32 v94, 0xff00, v94
	v_and_b32_e32 v95, 0xff0000, v95
	v_perm_b32 v93, v96, v93, s81
	v_or3_b32 v93, v93, v94, v95
	global_store_dwordx4 v[80:81], v[90:93], off offset:2048
	v_mul_f32_e32 v94, v147, v145
	v_rndne_f32_e32 v94, v94
	v_mul_f32_e32 v91, v147, v139
	v_mul_f32_e32 v90, v147, v138
	v_rndne_f32_e32 v91, v91
	v_mul_f32_e32 v92, v147, v140
	v_mul_f32_e32 v93, v147, v141
	v_rndne_f32_e32 v90, v90
	v_cvt_i32_f32_e32 v91, v91
	v_rndne_f32_e32 v92, v92
	v_rndne_f32_e32 v93, v93
	v_cvt_i32_f32_e32 v90, v90
	v_cvt_i32_f32_sdwa v92, v92 dst_sel:WORD_1 dst_unused:UNUSED_PAD src0_sel:DWORD
	v_cvt_i32_f32_e32 v93, v93
	v_lshlrev_b32_e32 v91, 8, v91
	v_and_b32_e32 v91, 0xff00, v91
	v_and_b32_e32 v92, 0xff0000, v92
	v_perm_b32 v90, v93, v90, s81
	v_or3_b32 v90, v90, v91, v92
	v_mul_f32_e32 v92, v147, v143
	v_mul_f32_e32 v91, v147, v142
	v_rndne_f32_e32 v92, v92
	v_mul_f32_e32 v93, v147, v144
	v_rndne_f32_e32 v91, v91
	v_cvt_i32_f32_e32 v92, v92
	v_rndne_f32_e32 v93, v93
	v_cvt_i32_f32_e32 v91, v91
	v_cvt_i32_f32_sdwa v93, v93 dst_sel:WORD_1 dst_unused:UNUSED_PAD src0_sel:DWORD
	v_cvt_i32_f32_e32 v94, v94
	v_lshlrev_b32_e32 v92, 8, v92
	v_and_b32_e32 v92, 0xff00, v92
	v_and_b32_e32 v93, 0xff0000, v93
	v_perm_b32 v91, v94, v91, s81
	v_mul_f32_e32 v86, v147, v86
	v_mul_f32_e32 v82, v147, v82
	v_or3_b32 v91, v91, v92, v93
	v_mul_f32_e32 v92, v147, v146
	v_rndne_f32_e32 v86, v86
	v_mul_f32_e32 v85, v147, v85
	v_mul_f32_e32 v84, v147, v84
	v_mul_f32_e32 v83, v147, v83
	v_rndne_f32_e32 v82, v82
	v_mul_f32_e32 v35, v147, v35
	v_mul_f32_e32 v0, v147, v0
	v_rndne_f32_e32 v92, v92
	v_cvt_i32_f32_e32 v86, v86
	v_rndne_f32_e32 v85, v85
	v_rndne_f32_e32 v84, v84
	v_rndne_f32_e32 v83, v83
	v_cvt_i32_f32_e32 v82, v82
	v_rndne_f32_e32 v35, v35
	v_rndne_f32_e32 v0, v0
	v_cvt_i32_f32_e32 v92, v92
	v_cvt_i32_f32_sdwa v85, v85 dst_sel:WORD_1 dst_unused:UNUSED_PAD src0_sel:DWORD
	v_cvt_i32_f32_e32 v84, v84
	v_cvt_i32_f32_e32 v83, v83
	v_cvt_i32_f32_sdwa v35, v35 dst_sel:WORD_1 dst_unused:UNUSED_PAD src0_sel:DWORD
	v_cvt_i32_f32_e32 v0, v0
	v_lshlrev_b32_e32 v86, 8, v86
	v_lshlrev_b32_e32 v82, 8, v82
	v_and_b32_e32 v86, 0xff00, v86
	v_and_b32_e32 v85, 0xff0000, v85
	v_perm_b32 v84, v84, v92, s81
	v_and_b32_e32 v82, 0xff00, v82
	v_and_b32_e32 v35, 0xff0000, v35
	v_perm_b32 v0, v0, v83, s81
	v_or3_b32 v92, v84, v86, v85
	v_or3_b32 v93, v0, v82, v35
	global_store_dwordx4 v[80:81], v[90:93], off offset:3072
	s_and_saveexec_b64 s[14:15], s[4:5]
	s_cbranch_execnz .LBB0_164
	s_or_b64 exec, exec, s[14:15]
	s_andn2_b64 vcc, exec, s[12:13]
	s_mov_b64 s[12:13], -1
	s_cbranch_vccnz .LBB0_159
	s_branch .LBB0_165

.LBB0_167:
	v_and_b32_e32 v91, 0xffff0000, v40
	v_lshlrev_b32_e32 v90, 16, v40
	v_mul_f32_e32 v87, v91, v91
	v_lshlrev_b32_e32 v92, 16, v41
	v_fmac_f32_e32 v87, v90, v90
	v_and_b32_e32 v93, 0xffff0000, v41
	v_fmac_f32_e32 v87, v92, v92
	v_lshlrev_b32_e32 v94, 16, v42
	v_fmac_f32_e32 v87, v93, v93
	v_and_b32_e32 v95, 0xffff0000, v42
	v_fmac_f32_e32 v87, v94, v94
	v_lshlrev_b32_e32 v96, 16, v43
	v_fmac_f32_e32 v87, v95, v95
	v_and_b32_e32 v97, 0xffff0000, v43
	v_fmac_f32_e32 v87, v96, v96
	v_lshlrev_b32_e32 v98, 16, v36
	v_fmac_f32_e32 v87, v97, v97
	v_and_b32_e32 v99, 0xffff0000, v36
	v_fmac_f32_e32 v87, v98, v98
	v_lshlrev_b32_e32 v100, 16, v37
	v_fmac_f32_e32 v87, v99, v99
	v_and_b32_e32 v101, 0xffff0000, v37
	v_fmac_f32_e32 v87, v100, v100
	v_lshlrev_b32_e32 v102, 16, v38
	v_fmac_f32_e32 v87, v101, v101
	v_and_b32_e32 v103, 0xffff0000, v38
	v_fmac_f32_e32 v87, v102, v102
	v_lshlrev_b32_e32 v104, 16, v39
	v_fmac_f32_e32 v87, v103, v103
	v_and_b32_e32 v105, 0xffff0000, v39
	v_fmac_f32_e32 v87, v104, v104
	v_lshlrev_b32_e32 v106, 16, v48
	v_fmac_f32_e32 v87, v105, v105
	v_and_b32_e32 v107, 0xffff0000, v48
	v_fmac_f32_e32 v87, v106, v106
	v_lshlrev_b32_e32 v108, 16, v49
	v_fmac_f32_e32 v87, v107, v107
	v_and_b32_e32 v109, 0xffff0000, v49
	v_fmac_f32_e32 v87, v108, v108
	v_lshlrev_b32_e32 v110, 16, v50
	v_fmac_f32_e32 v87, v109, v109
	v_and_b32_e32 v111, 0xffff0000, v50
	v_fmac_f32_e32 v87, v110, v110
	v_lshlrev_b32_e32 v112, 16, v51
	v_fmac_f32_e32 v87, v111, v111
	v_and_b32_e32 v113, 0xffff0000, v51
	v_fmac_f32_e32 v87, v112, v112
	v_max3_f32 v0, |v90|, 0, |v91|
	v_lshlrev_b32_e32 v114, 16, v44
	v_fmac_f32_e32 v87, v113, v113
	v_max3_f32 v0, v0, |v92|, |v93|
	v_and_b32_e32 v115, 0xffff0000, v44
	v_fmac_f32_e32 v87, v114, v114
	v_max3_f32 v0, v0, |v94|, |v95|
	v_lshlrev_b32_e32 v116, 16, v45
	v_fmac_f32_e32 v87, v115, v115
	v_max3_f32 v0, v0, |v96|, |v97|
	v_and_b32_e32 v117, 0xffff0000, v45
	v_fmac_f32_e32 v87, v116, v116
	v_max3_f32 v0, v0, |v98|, |v99|
	v_lshlrev_b32_e32 v118, 16, v46
	v_fmac_f32_e32 v87, v117, v117
	v_max3_f32 v0, v0, |v100|, |v101|
	v_and_b32_e32 v119, 0xffff0000, v46
	v_fmac_f32_e32 v87, v118, v118
	v_max3_f32 v0, v0, |v102|, |v103|
	v_lshlrev_b32_e32 v120, 16, v47
	v_fmac_f32_e32 v87, v119, v119
	v_max3_f32 v0, v0, |v104|, |v105|
	v_and_b32_e32 v121, 0xffff0000, v47
	v_fmac_f32_e32 v87, v120, v120
	v_max3_f32 v0, v0, |v106|, |v107|
	v_lshlrev_b32_e32 v122, 16, v56
	v_fmac_f32_e32 v87, v121, v121
	v_max3_f32 v0, v0, |v108|, |v109|
	v_and_b32_e32 v123, 0xffff0000, v56
	v_fmac_f32_e32 v87, v122, v122
	v_max3_f32 v0, v0, |v110|, |v111|
	v_lshlrev_b32_e32 v124, 16, v57
	v_fmac_f32_e32 v87, v123, v123
	v_max3_f32 v0, v0, |v112|, |v113|
	v_and_b32_e32 v125, 0xffff0000, v57
	v_fmac_f32_e32 v87, v124, v124
	v_max3_f32 v0, v0, |v114|, |v115|
	v_lshlrev_b32_e32 v126, 16, v58
	v_fmac_f32_e32 v87, v125, v125
	v_max3_f32 v0, v0, |v116|, |v117|
	v_and_b32_e32 v127, 0xffff0000, v58
	v_fmac_f32_e32 v87, v126, v126
	v_max3_f32 v0, v0, |v118|, |v119|
	v_lshlrev_b32_e32 v128, 16, v59
	v_fmac_f32_e32 v87, v127, v127
	v_max3_f32 v0, v0, |v120|, |v121|
	v_and_b32_e32 v129, 0xffff0000, v59
	v_fmac_f32_e32 v87, v128, v128
	v_lshlrev_b32_e32 v130, 16, v52
	v_max3_f32 v0, v0, |v122|, |v123|
	v_fmac_f32_e32 v87, v129, v129
	v_and_b32_e32 v131, 0xffff0000, v52
	v_max3_f32 v0, v0, |v124|, |v125|
	v_fmac_f32_e32 v87, v130, v130
	v_lshlrev_b32_e32 v132, 16, v53
	v_max3_f32 v0, v0, |v126|, |v127|
	v_fmac_f32_e32 v87, v131, v131
	v_and_b32_e32 v133, 0xffff0000, v53
	v_max3_f32 v0, v0, |v128|, |v129|
	v_fmac_f32_e32 v87, v132, v132
	v_lshlrev_b32_e32 v134, 16, v54
	v_max3_f32 v0, v0, |v130|, |v131|
	v_fmac_f32_e32 v87, v133, v133
	v_and_b32_e32 v135, 0xffff0000, v54
	v_max3_f32 v0, v0, |v132|, |v133|
	v_fmac_f32_e32 v87, v134, v134
	v_lshlrev_b32_e32 v136, 16, v55
	v_and_b32_e32 v137, 0xffff0000, v55
	v_max3_f32 v0, v0, |v134|, |v135|
	v_fmac_f32_e32 v87, v135, v135
	v_max3_f32 v80, v0, |v136|, |v137|
	v_lshlrev_b32_e32 v138, 16, v64
	v_and_b32_e32 v139, 0xffff0000, v64
	v_fmac_f32_e32 v87, v136, v136
	v_lshlrev_b32_e32 v140, 16, v65
	v_and_b32_e32 v141, 0xffff0000, v65
	v_max3_f32 v80, v80, |v138|, |v139|
	v_fmac_f32_e32 v87, v137, v137
	v_lshlrev_b32_e32 v142, 16, v66
	v_and_b32_e32 v143, 0xffff0000, v66
	v_max3_f32 v80, v80, |v140|, |v141|
	v_fmac_f32_e32 v87, v138, v138
	v_lshlrev_b32_e32 v144, 16, v67
	v_and_b32_e32 v145, 0xffff0000, v67
	v_max3_f32 v80, v80, |v142|, |v143|
	v_fmac_f32_e32 v87, v139, v139
	v_lshlrev_b32_e32 v146, 16, v60
	v_and_b32_e32 v86, 0xffff0000, v60
	v_max3_f32 v80, v80, |v144|, |v145|
	v_fmac_f32_e32 v87, v140, v140
	v_lshlrev_b32_e32 v85, 16, v61
	v_and_b32_e32 v84, 0xffff0000, v61
	v_max3_f32 v80, v80, |v146|, |v86|
	v_fmac_f32_e32 v87, v141, v141
	v_lshlrev_b32_e32 v83, 16, v62
	v_and_b32_e32 v82, 0xffff0000, v62
	v_max3_f32 v80, v80, |v85|, |v84|
	v_fmac_f32_e32 v87, v142, v142
	v_lshlrev_b32_e32 v35, 16, v63
	v_and_b32_e32 v0, 0xffff0000, v63
	v_max3_f32 v80, v80, |v83|, |v82|
	v_fmac_f32_e32 v87, v143, v143
	v_max3_f32 v80, v80, |v35|, |v0|
	v_fmac_f32_e32 v87, v144, v144
	s_nop 1
	v_mov_b32_dpp v81, v80 quad_perm:[1,0,3,2] row_mask:0xf bank_mask:0xf
	v_fmac_f32_e32 v87, v145, v145
	v_fmac_f32_e32 v87, v146, v146
	v_fmac_f32_e32 v87, v86, v86
	v_fmac_f32_e32 v87, v85, v85
	v_fmac_f32_e32 v87, v84, v84
	s_waitcnt lgkmcnt(0)
	v_max_f32_e32 v81, v81, v81
	v_fmac_f32_e32 v87, v83, v83
	v_max_f32_e32 v80, v80, v81
	v_fmac_f32_e32 v87, v82, v82
	s_nop 1
	v_mov_b32_dpp v81, v80 quad_perm:[2,3,0,1] row_mask:0xf bank_mask:0xf
	v_fmac_f32_e32 v87, v35, v35
	v_fmac_f32_e32 v87, v0, v0
	s_nop 1
	v_mov_b32_dpp v88, v87 quad_perm:[1,0,3,2] row_mask:0xf bank_mask:0xf
	s_waitcnt lgkmcnt(0)
	v_max_f32_e32 v81, v81, v81
	v_max_f32_e32 v80, v80, v81
	s_nop 1
	v_mov_b32_dpp v81, v80 row_shl:4 row_mask:0xf bank_mask:0x5
	v_mov_b32_dpp v81, v80 row_shr:4 row_mask:0xf bank_mask:0xa
	s_waitcnt lgkmcnt(0)
	v_add_f32_e32 v87, v87, v88
	s_nop 1
	v_mov_b32_dpp v88, v87 quad_perm:[2,3,0,1] row_mask:0xf bank_mask:0xf
	s_waitcnt lgkmcnt(0)
	v_max_f32_e32 v81, v81, v81
	v_max_f32_e32 v80, v80, v81
	s_waitcnt lgkmcnt(0)
	v_add_f32_e32 v87, v87, v88
	s_nop 1
	v_mov_b32_dpp v81, v80 row_ror:8 row_mask:0xf bank_mask:0xf
	s_nop 1
	v_mov_b32_dpp v88, v87 row_shl:4 row_mask:0xf bank_mask:0x5
	v_mov_b32_dpp v88, v87 row_shr:4 row_mask:0xf bank_mask:0xa
	s_waitcnt lgkmcnt(0)
	v_max_f32_e32 v81, v81, v81
	s_waitcnt lgkmcnt(0)
	v_add_f32_e32 v87, v87, v88
	v_max_f32_e32 v80, v80, v81
	s_nop 1
	v_mov_b32_dpp v88, v87 row_ror:8 row_mask:0xf bank_mask:0xf
	ds_swizzle_b32 v81, v80 offset:swizzle(SWAP,16)
	s_waitcnt lgkmcnt(0)
	v_add_f32_e32 v87, v87, v88
	s_waitcnt lgkmcnt(0)
	v_max_f32_e32 v81, v81, v81
	ds_swizzle_b32 v88, v87 offset:swizzle(SWAP,16)
	v_max_f32_e32 v80, v80, v81
	v_mov_b32_e32 v81, v80
	s_nop 1
	v_permlane32_swap_b32_e32 v80, v81
	v_max_f32_e32 v81, v81, v81
	v_max_f32_e32 v80, v80, v80
	s_waitcnt lgkmcnt(0)
	v_add_f32_e32 v88, v87, v88
	v_max_f32_e32 v87, v80, v81
	v_div_scale_f32 v80, s[6:7], v87, v87, s79
	v_rcp_f32_e32 v81, v80
	v_mov_b32_e32 v89, v88
	s_nop 1
	v_permlane32_swap_b32_e32 v88, v89
	v_fma_f32 v147, -v80, v81, 1.0
	v_fmac_f32_e32 v81, v147, v81
	v_div_scale_f32 v147, vcc, s79, v87, s79
	v_mul_f32_e32 v148, v147, v81
	v_fma_f32 v149, -v80, v148, v147
	v_fmac_f32_e32 v148, v149, v81
	v_fma_f32 v80, -v80, v148, v147
	v_div_fmas_f32 v80, v80, v81, v148
	v_div_fixup_f32 v80, v80, v87, s79
	v_cmp_lt_f32_e32 vcc, 0, v87
	s_nop 1
	v_cndmask_b32_e32 v147, 0, v80, vcc
	v_mul_f32_e32 v91, v147, v91
	v_mul_f32_e32 v90, v147, v90
	v_rndne_f32_e32 v91, v91
	v_mul_f32_e32 v92, v147, v92
	v_mul_f32_e32 v93, v147, v93
	v_rndne_f32_e32 v90, v90
	v_cvt_i32_f32_e32 v91, v91
	v_rndne_f32_e32 v92, v92
	v_rndne_f32_e32 v93, v93
	v_cvt_i32_f32_e32 v90, v90
	v_cvt_i32_f32_sdwa v92, v92 dst_sel:WORD_1 dst_unused:UNUSED_PAD src0_sel:DWORD
	v_cvt_i32_f32_e32 v93, v93
	v_lshlrev_b32_e32 v91, 8, v91
	v_and_b32_e32 v91, 0xff00, v91
	v_and_b32_e32 v92, 0xff0000, v92
	v_perm_b32 v90, v93, v90, s81
	v_or3_b32 v90, v90, v91, v92
	v_mul_f32_e32 v92, v147, v95
	v_mul_f32_e32 v91, v147, v94
	v_rndne_f32_e32 v92, v92
	v_mul_f32_e32 v93, v147, v96
	v_mul_f32_e32 v94, v147, v97
	v_rndne_f32_e32 v91, v91
	v_cvt_i32_f32_e32 v92, v92
	v_rndne_f32_e32 v93, v93
	v_rndne_f32_e32 v94, v94
	v_cvt_i32_f32_e32 v91, v91
	v_cvt_i32_f32_sdwa v93, v93 dst_sel:WORD_1 dst_unused:UNUSED_PAD src0_sel:DWORD
	v_cvt_i32_f32_e32 v94, v94
	v_lshlrev_b32_e32 v92, 8, v92
	v_and_b32_e32 v92, 0xff00, v92
	v_and_b32_e32 v93, 0xff0000, v93
	v_perm_b32 v91, v94, v91, s81
	v_or3_b32 v91, v91, v92, v93
	v_mul_f32_e32 v93, v147, v99
	v_mul_f32_e32 v92, v147, v98
	v_rndne_f32_e32 v93, v93
	v_mul_f32_e32 v94, v147, v100
	v_mul_f32_e32 v95, v147, v101
	v_rndne_f32_e32 v92, v92
	v_cvt_i32_f32_e32 v93, v93
	v_rndne_f32_e32 v94, v94
	v_rndne_f32_e32 v95, v95
	v_cvt_i32_f32_e32 v92, v92
	v_cvt_i32_f32_sdwa v94, v94 dst_sel:WORD_1 dst_unused:UNUSED_PAD src0_sel:DWORD
	v_cvt_i32_f32_e32 v95, v95
	v_lshlrev_b32_e32 v93, 8, v93
	v_and_b32_e32 v93, 0xff00, v93
	v_and_b32_e32 v94, 0xff0000, v94
	v_perm_b32 v92, v95, v92, s81
	v_or3_b32 v92, v92, v93, v94
	v_mul_f32_e32 v94, v147, v103
	v_mul_f32_e32 v93, v147, v102
	v_rndne_f32_e32 v94, v94
	v_mul_f32_e32 v95, v147, v104
	v_mul_f32_e32 v96, v147, v105
	v_rndne_f32_e32 v93, v93
	v_cvt_i32_f32_e32 v94, v94
	v_rndne_f32_e32 v95, v95
	v_rndne_f32_e32 v96, v96
	v_cvt_i32_f32_e32 v93, v93
	v_cvt_i32_f32_sdwa v95, v95 dst_sel:WORD_1 dst_unused:UNUSED_PAD src0_sel:DWORD
	v_cvt_i32_f32_e32 v96, v96
	v_lshl_add_u64 v[80:81], s[8:9], 0, v[72:73]
	v_lshlrev_b32_e32 v94, 8, v94
	v_and_b32_e32 v94, 0xff00, v94
	v_and_b32_e32 v95, 0xff0000, v95
	v_perm_b32 v93, v96, v93, s81
	v_add_co_u32_e32 v80, vcc, s20, v80
	v_or3_b32 v93, v93, v94, v95
	s_nop 0
	v_addc_co_u32_e32 v81, vcc, 0, v81, vcc
	global_store_dwordx4 v[80:81], v[90:93], off
	v_mul_f32_e32 v94, v147, v113
	v_rndne_f32_e32 v94, v94
	v_mul_f32_e32 v91, v147, v107
	v_mul_f32_e32 v90, v147, v106
	v_rndne_f32_e32 v91, v91
	v_mul_f32_e32 v92, v147, v108
	v_mul_f32_e32 v93, v147, v109
	v_rndne_f32_e32 v90, v90
	v_cvt_i32_f32_e32 v91, v91
	v_rndne_f32_e32 v92, v92
	v_rndne_f32_e32 v93, v93
	v_cvt_i32_f32_e32 v90, v90
	v_cvt_i32_f32_sdwa v92, v92 dst_sel:WORD_1 dst_unused:UNUSED_PAD src0_sel:DWORD
	v_cvt_i32_f32_e32 v93, v93
	v_lshlrev_b32_e32 v91, 8, v91
	v_and_b32_e32 v91, 0xff00, v91
	v_and_b32_e32 v92, 0xff0000, v92
	v_perm_b32 v90, v93, v90, s81
	v_or3_b32 v90, v90, v91, v92
	v_mul_f32_e32 v92, v147, v111
	v_mul_f32_e32 v91, v147, v110
	v_rndne_f32_e32 v92, v92
	v_mul_f32_e32 v93, v147, v112
	v_rndne_f32_e32 v91, v91
	v_cvt_i32_f32_e32 v92, v92
	v_rndne_f32_e32 v93, v93
	v_cvt_i32_f32_e32 v91, v91
	v_cvt_i32_f32_sdwa v93, v93 dst_sel:WORD_1 dst_unused:UNUSED_PAD src0_sel:DWORD
	v_cvt_i32_f32_e32 v94, v94
	v_lshlrev_b32_e32 v92, 8, v92
	v_and_b32_e32 v92, 0xff00, v92
	v_and_b32_e32 v93, 0xff0000, v93
	v_perm_b32 v91, v94, v91, s81
	v_or3_b32 v91, v91, v92, v93
	v_mul_f32_e32 v93, v147, v115
	v_mul_f32_e32 v92, v147, v114
	v_rndne_f32_e32 v93, v93
	v_mul_f32_e32 v94, v147, v116
	v_mul_f32_e32 v95, v147, v117
	v_rndne_f32_e32 v92, v92
	v_cvt_i32_f32_e32 v93, v93
	v_rndne_f32_e32 v94, v94
	v_rndne_f32_e32 v95, v95
	v_cvt_i32_f32_e32 v92, v92
	v_cvt_i32_f32_sdwa v94, v94 dst_sel:WORD_1 dst_unused:UNUSED_PAD src0_sel:DWORD
	v_cvt_i32_f32_e32 v95, v95
	v_lshlrev_b32_e32 v93, 8, v93
	v_and_b32_e32 v93, 0xff00, v93
	v_and_b32_e32 v94, 0xff0000, v94
	v_perm_b32 v92, v95, v92, s81
	v_or3_b32 v92, v92, v93, v94
	v_mul_f32_e32 v94, v147, v119
	v_mul_f32_e32 v93, v147, v118
	v_rndne_f32_e32 v94, v94
	v_mul_f32_e32 v95, v147, v120
	v_mul_f32_e32 v96, v147, v121
	v_rndne_f32_e32 v93, v93
	v_cvt_i32_f32_e32 v94, v94
	v_rndne_f32_e32 v95, v95
	v_rndne_f32_e32 v96, v96
	v_cvt_i32_f32_e32 v93, v93
	v_cvt_i32_f32_sdwa v95, v95 dst_sel:WORD_1 dst_unused:UNUSED_PAD src0_sel:DWORD
	v_cvt_i32_f32_e32 v96, v96
	v_lshlrev_b32_e32 v94, 8, v94
	v_and_b32_e32 v94, 0xff00, v94
	v_and_b32_e32 v95, 0xff0000, v95
	v_perm_b32 v93, v96, v93, s81
	v_or3_b32 v93, v93, v94, v95
	global_store_dwordx4 v[80:81], v[90:93], off offset:1024
	v_mul_f32_e32 v94, v147, v129
	v_rndne_f32_e32 v94, v94
	v_mul_f32_e32 v91, v147, v123
	v_mul_f32_e32 v90, v147, v122
	v_rndne_f32_e32 v91, v91
	v_mul_f32_e32 v92, v147, v124
	v_mul_f32_e32 v93, v147, v125
	v_rndne_f32_e32 v90, v90
	v_cvt_i32_f32_e32 v91, v91
	v_rndne_f32_e32 v92, v92
	v_rndne_f32_e32 v93, v93
	v_cvt_i32_f32_e32 v90, v90
	v_cvt_i32_f32_sdwa v92, v92 dst_sel:WORD_1 dst_unused:UNUSED_PAD src0_sel:DWORD
	v_cvt_i32_f32_e32 v93, v93
	v_lshlrev_b32_e32 v91, 8, v91
	v_and_b32_e32 v91, 0xff00, v91
	v_and_b32_e32 v92, 0xff0000, v92
	v_perm_b32 v90, v93, v90, s81
	v_or3_b32 v90, v90, v91, v92
	v_mul_f32_e32 v92, v147, v127
	v_mul_f32_e32 v91, v147, v126
	v_rndne_f32_e32 v92, v92
	v_mul_f32_e32 v93, v147, v128
	v_rndne_f32_e32 v91, v91
	v_cvt_i32_f32_e32 v92, v92
	v_rndne_f32_e32 v93, v93
	v_cvt_i32_f32_e32 v91, v91
	v_cvt_i32_f32_sdwa v93, v93 dst_sel:WORD_1 dst_unused:UNUSED_PAD src0_sel:DWORD
	v_cvt_i32_f32_e32 v94, v94
	v_lshlrev_b32_e32 v92, 8, v92
	v_and_b32_e32 v92, 0xff00, v92
	v_and_b32_e32 v93, 0xff0000, v93
	v_perm_b32 v91, v94, v91, s81
	v_or3_b32 v91, v91, v92, v93
	v_mul_f32_e32 v93, v147, v131
	v_mul_f32_e32 v92, v147, v130
	v_rndne_f32_e32 v93, v93
	v_mul_f32_e32 v94, v147, v132
	v_mul_f32_e32 v95, v147, v133
	v_rndne_f32_e32 v92, v92
	v_cvt_i32_f32_e32 v93, v93
	v_rndne_f32_e32 v94, v94
	v_rndne_f32_e32 v95, v95
	v_cvt_i32_f32_e32 v92, v92
	v_cvt_i32_f32_sdwa v94, v94 dst_sel:WORD_1 dst_unused:UNUSED_PAD src0_sel:DWORD
	v_cvt_i32_f32_e32 v95, v95
	v_lshlrev_b32_e32 v93, 8, v93
	v_and_b32_e32 v93, 0xff00, v93
	v_and_b32_e32 v94, 0xff0000, v94
	v_perm_b32 v92, v95, v92, s81
	v_or3_b32 v92, v92, v93, v94
	v_mul_f32_e32 v94, v147, v135
	v_mul_f32_e32 v93, v147, v134
	v_rndne_f32_e32 v94, v94
	v_mul_f32_e32 v95, v147, v136
	v_mul_f32_e32 v96, v147, v137
	v_rndne_f32_e32 v93, v93
	v_cvt_i32_f32_e32 v94, v94
	v_rndne_f32_e32 v95, v95
	v_rndne_f32_e32 v96, v96
	v_cvt_i32_f32_e32 v93, v93
	v_cvt_i32_f32_sdwa v95, v95 dst_sel:WORD_1 dst_unused:UNUSED_PAD src0_sel:DWORD
	v_cvt_i32_f32_e32 v96, v96
	v_lshlrev_b32_e32 v94, 8, v94
	v_and_b32_e32 v94, 0xff00, v94
	v_and_b32_e32 v95, 0xff0000, v95
	v_perm_b32 v93, v96, v93, s81
	v_or3_b32 v93, v93, v94, v95
	global_store_dwordx4 v[80:81], v[90:93], off offset:2048
	v_mul_f32_e32 v94, v147, v145
	v_rndne_f32_e32 v94, v94
	v_mul_f32_e32 v91, v147, v139
	v_mul_f32_e32 v90, v147, v138
	v_rndne_f32_e32 v91, v91
	v_mul_f32_e32 v92, v147, v140
	v_mul_f32_e32 v93, v147, v141
	v_rndne_f32_e32 v90, v90
	v_cvt_i32_f32_e32 v91, v91
	v_rndne_f32_e32 v92, v92
	v_rndne_f32_e32 v93, v93
	v_cvt_i32_f32_e32 v90, v90
	v_cvt_i32_f32_sdwa v92, v92 dst_sel:WORD_1 dst_unused:UNUSED_PAD src0_sel:DWORD
	v_cvt_i32_f32_e32 v93, v93
	v_lshlrev_b32_e32 v91, 8, v91
	v_and_b32_e32 v91, 0xff00, v91
	v_and_b32_e32 v92, 0xff0000, v92
	v_perm_b32 v90, v93, v90, s81
	v_or3_b32 v90, v90, v91, v92
	v_mul_f32_e32 v92, v147, v143
	v_mul_f32_e32 v91, v147, v142
	v_rndne_f32_e32 v92, v92
	v_mul_f32_e32 v93, v147, v144
	v_rndne_f32_e32 v91, v91
	v_cvt_i32_f32_e32 v92, v92
	v_rndne_f32_e32 v93, v93
	v_cvt_i32_f32_e32 v91, v91
	v_cvt_i32_f32_sdwa v93, v93 dst_sel:WORD_1 dst_unused:UNUSED_PAD src0_sel:DWORD
	v_cvt_i32_f32_e32 v94, v94
	v_lshlrev_b32_e32 v92, 8, v92
	v_and_b32_e32 v92, 0xff00, v92
	v_and_b32_e32 v93, 0xff0000, v93
	v_perm_b32 v91, v94, v91, s81
	v_mul_f32_e32 v86, v147, v86
	v_mul_f32_e32 v82, v147, v82
	v_or3_b32 v91, v91, v92, v93
	v_mul_f32_e32 v92, v147, v146
	v_rndne_f32_e32 v86, v86
	v_mul_f32_e32 v85, v147, v85
	v_mul_f32_e32 v84, v147, v84
	v_mul_f32_e32 v83, v147, v83
	v_rndne_f32_e32 v82, v82
	v_mul_f32_e32 v35, v147, v35
	v_mul_f32_e32 v0, v147, v0
	v_rndne_f32_e32 v92, v92
	v_cvt_i32_f32_e32 v86, v86
	v_rndne_f32_e32 v85, v85
	v_rndne_f32_e32 v84, v84
	v_rndne_f32_e32 v83, v83
	v_cvt_i32_f32_e32 v82, v82
	v_rndne_f32_e32 v35, v35
	v_rndne_f32_e32 v0, v0
	v_cvt_i32_f32_e32 v92, v92
	v_cvt_i32_f32_sdwa v85, v85 dst_sel:WORD_1 dst_unused:UNUSED_PAD src0_sel:DWORD
	v_cvt_i32_f32_e32 v84, v84
	v_cvt_i32_f32_e32 v83, v83
	v_cvt_i32_f32_sdwa v35, v35 dst_sel:WORD_1 dst_unused:UNUSED_PAD src0_sel:DWORD
	v_cvt_i32_f32_e32 v0, v0
	v_lshlrev_b32_e32 v86, 8, v86
	v_lshlrev_b32_e32 v82, 8, v82
	v_and_b32_e32 v86, 0xff00, v86
	v_and_b32_e32 v85, 0xff0000, v85
	v_perm_b32 v84, v84, v92, s81
	v_and_b32_e32 v82, 0xff00, v82
	v_and_b32_e32 v35, 0xff0000, v35
	v_perm_b32 v0, v0, v83, s81
	v_or3_b32 v92, v84, v86, v85
	v_or3_b32 v93, v0, v82, v35
	global_store_dwordx4 v[80:81], v[90:93], off offset:3072
	s_and_saveexec_b64 s[14:15], s[4:5]
	s_cbranch_execz .LBB0_158
	v_add_f32_e32 v0, v88, v89
	v_fmamk_f32 v0, v0, 0x39800000, v214
	v_mul_f32_e32 v35, 0x4f800000, v0
	v_cmp_gt_f32_e32 vcc, s29, v0
	s_nop 1
	v_cndmask_b32_e32 v0, v0, v35, vcc
	v_sqrt_f32_e32 v35, v0
	s_nop 0
	v_add_u32_e32 v80, -1, v35
	v_fma_f32 v82, -v80, v35, v0
	v_add_u32_e32 v81, 1, v35
	v_cmp_ge_f32_e64 s[6:7], 0, v82
	v_mul_f32_e32 v82, 0x3c010204, v87
	s_nop 0
	v_cndmask_b32_e64 v80, v35, v80, s[6:7]
	v_fma_f32 v35, -v81, v35, v0
	v_cmp_lt_f32_e64 s[6:7], 0, v35
	s_nop 1
	v_cndmask_b32_e64 v35, v80, v81, s[6:7]
	v_mul_f32_e32 v80, 0x37800000, v35
	v_cndmask_b32_e32 v35, v35, v80, vcc
	v_cmp_class_f32_e32 vcc, v0, v252
	s_nop 1
	v_cndmask_b32_e32 v0, v35, v0, vcc
	v_div_scale_f32 v35, s[6:7], v0, v0, 1.0
	v_rcp_f32_e32 v80, v35
	s_nop 0
	v_fma_f32 v81, -v35, v80, 1.0
	v_fmac_f32_e32 v80, v81, v80
	v_div_scale_f32 v81, vcc, 1.0, v0, 1.0
	v_mul_f32_e32 v83, v81, v80
	v_fma_f32 v84, -v35, v83, v81
	v_fmac_f32_e32 v83, v84, v80
	v_fma_f32 v35, -v35, v83, v81
	v_div_fmas_f32 v35, v35, v80, v83
	v_lshl_add_u64 v[80:81], s[8:9], 0, v[76:77]
	v_div_fixup_f32 v0, v35, v0, 1.0
	v_readfirstlane_b32 s6, v80
	v_readfirstlane_b32 s7, v81
	v_mov_b32_e32 v35, 0x5fd00000
	s_nop 3
	global_store_dword v35, v0, s[6:7]
	v_mul_f32_e32 v0, v82, v0
	v_mov_b32_e32 v35, 0x5fd08000
	global_store_dword v35, v0, s[6:7]
	s_branch .LBB0_158

.LBB0_931:
	s_nop 0
	s_nop 0
	s_nop 0
	s_nop 0
	s_nop 0
	s_nop 0
	s_nop 0
	s_nop 0
	s_mov_b32 s8, -1
	s_waitcnt vmcnt(0)
	s_waitcnt vmcnt(0) lgkmcnt(0)
	s_barrier
	s_nop 0
	v_mbcnt_lo_u32_b32 v0, s8, 0
	v_mbcnt_hi_u32_b32 v0, s8, v0
	v_add_u32_e32 v0, s76, v0
	s_nop 0
	v_cmp_eq_u32_e32 vcc, 0, v0
	s_and_saveexec_b64 s[10:11], vcc
	s_cbranch_execz .LBB0_983
	v_readlane_b32 s9, v255, 3
	s_getreg_b32 s8, hwreg(HW_REG_XCC_ID, 0, 4)
	s_waitcnt vmcnt(0) expcnt(0) lgkmcnt(0)
	v_mov_b32_e32 v0, s9
	ds_read_b32 v3, v0
	v_readlane_b32 s9, v255, 4
	s_and_b32 s8, s8, 15
	s_waitcnt lgkmcnt(0)
	v_cmp_ne_u32_e32 vcc, 0, v3
	v_mov_b32_e32 v0, s9
	ds_read_b32 v2, v0
	s_cbranch_vccnz .LBB0_947
	s_mov_b32 s9, 1
	s_branch .LBB0_935

.LBB0_994:
	s_waitcnt vmcnt(1)
	v_and_b32_e32 v91, 0xffff0000, v14
	v_lshlrev_b32_e32 v90, 16, v14
	v_mul_f32_e32 v87, v91, v91
	v_lshlrev_b32_e32 v92, 16, v15
	v_fmac_f32_e32 v87, v90, v90
	v_and_b32_e32 v93, 0xffff0000, v15
	v_fmac_f32_e32 v87, v92, v92
	v_lshlrev_b32_e32 v94, 16, v16
	v_fmac_f32_e32 v87, v93, v93
	v_and_b32_e32 v95, 0xffff0000, v16
	v_fmac_f32_e32 v87, v94, v94
	v_lshlrev_b32_e32 v96, 16, v17
	v_fmac_f32_e32 v87, v95, v95
	v_and_b32_e32 v97, 0xffff0000, v17
	v_fmac_f32_e32 v87, v96, v96
	v_lshlrev_b32_e32 v98, 16, v2
	v_fmac_f32_e32 v87, v97, v97
	v_and_b32_e32 v99, 0xffff0000, v2
	v_fmac_f32_e32 v87, v98, v98
	v_lshlrev_b32_e32 v100, 16, v3
	v_fmac_f32_e32 v87, v99, v99
	v_and_b32_e32 v101, 0xffff0000, v3
	v_fmac_f32_e32 v87, v100, v100
	v_lshlrev_b32_e32 v102, 16, v4
	v_fmac_f32_e32 v87, v101, v101
	v_and_b32_e32 v103, 0xffff0000, v4
	v_fmac_f32_e32 v87, v102, v102
	v_lshlrev_b32_e32 v104, 16, v5
	v_fmac_f32_e32 v87, v103, v103
	v_and_b32_e32 v105, 0xffff0000, v5
	v_fmac_f32_e32 v87, v104, v104
	v_lshlrev_b32_e32 v106, 16, v6
	v_fmac_f32_e32 v87, v105, v105
	v_and_b32_e32 v107, 0xffff0000, v6
	v_fmac_f32_e32 v87, v106, v106
	v_lshlrev_b32_e32 v108, 16, v7
	v_fmac_f32_e32 v87, v107, v107
	v_and_b32_e32 v109, 0xffff0000, v7
	v_fmac_f32_e32 v87, v108, v108
	v_lshlrev_b32_e32 v110, 16, v8
	v_fmac_f32_e32 v87, v109, v109
	v_and_b32_e32 v111, 0xffff0000, v8
	v_fmac_f32_e32 v87, v110, v110
	v_lshlrev_b32_e32 v112, 16, v9
	v_fmac_f32_e32 v87, v111, v111
	v_and_b32_e32 v113, 0xffff0000, v9
	v_fmac_f32_e32 v87, v112, v112
	v_max3_f32 v0, |v90|, 0, |v91|
	v_lshlrev_b32_e32 v114, 16, v10
	v_fmac_f32_e32 v87, v113, v113
	v_max3_f32 v0, v0, |v92|, |v93|
	v_and_b32_e32 v115, 0xffff0000, v10
	v_fmac_f32_e32 v87, v114, v114
	v_max3_f32 v0, v0, |v94|, |v95|
	v_lshlrev_b32_e32 v116, 16, v11
	v_fmac_f32_e32 v87, v115, v115
	v_max3_f32 v0, v0, |v96|, |v97|
	v_and_b32_e32 v117, 0xffff0000, v11
	v_fmac_f32_e32 v87, v116, v116
	v_max3_f32 v0, v0, |v98|, |v99|
	v_lshlrev_b32_e32 v118, 16, v12
	v_fmac_f32_e32 v87, v117, v117
	v_max3_f32 v0, v0, |v100|, |v101|
	v_and_b32_e32 v119, 0xffff0000, v12
	v_fmac_f32_e32 v87, v118, v118
	v_max3_f32 v0, v0, |v102|, |v103|
	v_lshlrev_b32_e32 v120, 16, v13
	v_fmac_f32_e32 v87, v119, v119
	v_max3_f32 v0, v0, |v104|, |v105|
	v_and_b32_e32 v121, 0xffff0000, v13
	v_fmac_f32_e32 v87, v120, v120
	v_max3_f32 v0, v0, |v106|, |v107|
	v_lshlrev_b32_e32 v122, 16, v22
	v_fmac_f32_e32 v87, v121, v121
	v_max3_f32 v0, v0, |v108|, |v109|
	v_and_b32_e32 v123, 0xffff0000, v22
	v_fmac_f32_e32 v87, v122, v122
	v_max3_f32 v0, v0, |v110|, |v111|
	v_lshlrev_b32_e32 v124, 16, v23
	v_fmac_f32_e32 v87, v123, v123
	v_max3_f32 v0, v0, |v112|, |v113|
	v_and_b32_e32 v125, 0xffff0000, v23
	v_fmac_f32_e32 v87, v124, v124
	v_max3_f32 v0, v0, |v114|, |v115|
	v_lshlrev_b32_e32 v126, 16, v24
	v_fmac_f32_e32 v87, v125, v125
	v_max3_f32 v0, v0, |v116|, |v117|
	v_and_b32_e32 v127, 0xffff0000, v24
	v_fmac_f32_e32 v87, v126, v126
	v_max3_f32 v0, v0, |v118|, |v119|
	v_lshlrev_b32_e32 v128, 16, v25
	v_fmac_f32_e32 v87, v127, v127
	v_max3_f32 v0, v0, |v120|, |v121|
	v_and_b32_e32 v129, 0xffff0000, v25
	v_fmac_f32_e32 v87, v128, v128
	v_lshlrev_b32_e32 v130, 16, v18
	v_max3_f32 v0, v0, |v122|, |v123|
	v_fmac_f32_e32 v87, v129, v129
	v_and_b32_e32 v131, 0xffff0000, v18
	v_max3_f32 v0, v0, |v124|, |v125|
	v_fmac_f32_e32 v87, v130, v130
	v_lshlrev_b32_e32 v132, 16, v19
	v_max3_f32 v0, v0, |v126|, |v127|
	v_fmac_f32_e32 v87, v131, v131
	v_and_b32_e32 v133, 0xffff0000, v19
	v_max3_f32 v0, v0, |v128|, |v129|
	v_fmac_f32_e32 v87, v132, v132
	v_lshlrev_b32_e32 v134, 16, v20
	v_max3_f32 v0, v0, |v130|, |v131|
	v_fmac_f32_e32 v87, v133, v133
	v_and_b32_e32 v135, 0xffff0000, v20
	v_max3_f32 v0, v0, |v132|, |v133|
	v_fmac_f32_e32 v87, v134, v134
	v_lshlrev_b32_e32 v136, 16, v21
	v_and_b32_e32 v137, 0xffff0000, v21
	v_max3_f32 v0, v0, |v134|, |v135|
	v_fmac_f32_e32 v87, v135, v135
	v_max3_f32 v80, v0, |v136|, |v137|
	v_lshlrev_b32_e32 v138, 16, v26
	v_and_b32_e32 v139, 0xffff0000, v26
	v_fmac_f32_e32 v87, v136, v136
	v_lshlrev_b32_e32 v140, 16, v27
	v_and_b32_e32 v141, 0xffff0000, v27
	v_max3_f32 v80, v80, |v138|, |v139|
	v_fmac_f32_e32 v87, v137, v137
	v_lshlrev_b32_e32 v142, 16, v28
	v_and_b32_e32 v143, 0xffff0000, v28
	v_max3_f32 v80, v80, |v140|, |v141|
	v_fmac_f32_e32 v87, v138, v138
	v_lshlrev_b32_e32 v144, 16, v29
	v_and_b32_e32 v145, 0xffff0000, v29
	v_max3_f32 v80, v80, |v142|, |v143|
	v_fmac_f32_e32 v87, v139, v139
	s_waitcnt vmcnt(0)
	v_lshlrev_b32_e32 v146, 16, v30
	v_and_b32_e32 v86, 0xffff0000, v30
	v_max3_f32 v80, v80, |v144|, |v145|
	v_fmac_f32_e32 v87, v140, v140
	v_lshlrev_b32_e32 v85, 16, v31
	v_and_b32_e32 v84, 0xffff0000, v31
	v_max3_f32 v80, v80, |v146|, |v86|
	v_fmac_f32_e32 v87, v141, v141
	v_lshlrev_b32_e32 v83, 16, v32
	v_and_b32_e32 v82, 0xffff0000, v32
	v_max3_f32 v80, v80, |v85|, |v84|
	v_fmac_f32_e32 v87, v142, v142
	v_lshlrev_b32_e32 v35, 16, v33
	v_and_b32_e32 v0, 0xffff0000, v33
	v_max3_f32 v80, v80, |v83|, |v82|
	v_fmac_f32_e32 v87, v143, v143
	v_max3_f32 v80, v80, |v35|, |v0|
	v_fmac_f32_e32 v87, v144, v144
	s_nop 1
	v_mov_b32_dpp v81, v80 quad_perm:[1,0,3,2] row_mask:0xf bank_mask:0xf
	v_fmac_f32_e32 v87, v145, v145
	v_fmac_f32_e32 v87, v146, v146
	v_fmac_f32_e32 v87, v86, v86
	v_fmac_f32_e32 v87, v85, v85
	v_fmac_f32_e32 v87, v84, v84
	s_waitcnt lgkmcnt(0)
	v_max_f32_e32 v81, v81, v81
	v_fmac_f32_e32 v87, v83, v83
	v_max_f32_e32 v80, v80, v81
	v_fmac_f32_e32 v87, v82, v82
	s_nop 1
	v_mov_b32_dpp v81, v80 quad_perm:[2,3,0,1] row_mask:0xf bank_mask:0xf
	v_fmac_f32_e32 v87, v35, v35
	v_fmac_f32_e32 v87, v0, v0
	s_nop 1
	v_mov_b32_dpp v88, v87 quad_perm:[1,0,3,2] row_mask:0xf bank_mask:0xf
	s_waitcnt lgkmcnt(0)
	v_max_f32_e32 v81, v81, v81
	v_max_f32_e32 v80, v80, v81
	s_nop 1
	v_mov_b32_dpp v81, v80 row_shl:4 row_mask:0xf bank_mask:0x5
	v_mov_b32_dpp v81, v80 row_shr:4 row_mask:0xf bank_mask:0xa
	s_waitcnt lgkmcnt(0)
	v_add_f32_e32 v87, v87, v88
	s_nop 1
	v_mov_b32_dpp v88, v87 quad_perm:[2,3,0,1] row_mask:0xf bank_mask:0xf
	s_waitcnt lgkmcnt(0)
	v_max_f32_e32 v81, v81, v81
	v_max_f32_e32 v80, v80, v81
	s_waitcnt lgkmcnt(0)
	v_add_f32_e32 v87, v87, v88
	s_nop 1
	v_mov_b32_dpp v81, v80 row_ror:8 row_mask:0xf bank_mask:0xf
	s_nop 1
	v_mov_b32_dpp v88, v87 row_shl:4 row_mask:0xf bank_mask:0x5
	v_mov_b32_dpp v88, v87 row_shr:4 row_mask:0xf bank_mask:0xa
	s_waitcnt lgkmcnt(0)
	v_max_f32_e32 v81, v81, v81
	s_waitcnt lgkmcnt(0)
	v_add_f32_e32 v87, v87, v88
	v_max_f32_e32 v80, v80, v81
	s_nop 1
	v_mov_b32_dpp v88, v87 row_ror:8 row_mask:0xf bank_mask:0xf
	ds_swizzle_b32 v81, v80 offset:swizzle(SWAP,16)
	s_waitcnt lgkmcnt(0)
	v_add_f32_e32 v87, v87, v88
	s_waitcnt lgkmcnt(0)
	v_max_f32_e32 v81, v81, v81
	ds_swizzle_b32 v88, v87 offset:swizzle(SWAP,16)
	v_max_f32_e32 v80, v80, v81
	v_mov_b32_e32 v81, v80
	s_nop 1
	v_permlane32_swap_b32_e32 v80, v81
	v_max_f32_e32 v81, v81, v81
	v_max_f32_e32 v80, v80, v80
	s_waitcnt lgkmcnt(0)
	v_add_f32_e32 v88, v87, v88
	v_max_f32_e32 v87, v80, v81
	v_div_scale_f32 v80, s[12:13], v87, v87, s79
	v_rcp_f32_e32 v81, v80
	v_mov_b32_e32 v89, v88
	s_nop 1
	v_permlane32_swap_b32_e32 v88, v89
	v_fma_f32 v147, -v80, v81, 1.0
	v_fmac_f32_e32 v81, v147, v81
	v_div_scale_f32 v147, vcc, s79, v87, s79
	v_mul_f32_e32 v148, v147, v81
	v_fma_f32 v149, -v80, v148, v147
	v_fmac_f32_e32 v148, v149, v81
	v_fma_f32 v80, -v80, v148, v147
	v_div_fmas_f32 v80, v80, v81, v148
	v_div_fixup_f32 v80, v80, v87, s79
	v_cmp_lt_f32_e32 vcc, 0, v87
	s_nop 1
	v_cndmask_b32_e32 v147, 0, v80, vcc
	v_mul_f32_e32 v91, v147, v91
	v_mul_f32_e32 v90, v147, v90
	v_rndne_f32_e32 v91, v91
	v_mul_f32_e32 v92, v147, v92
	v_mul_f32_e32 v93, v147, v93
	v_rndne_f32_e32 v90, v90
	v_cvt_i32_f32_e32 v91, v91
	v_rndne_f32_e32 v92, v92
	v_rndne_f32_e32 v93, v93
	v_cvt_i32_f32_e32 v90, v90
	v_cvt_i32_f32_sdwa v92, v92 dst_sel:WORD_1 dst_unused:UNUSED_PAD src0_sel:DWORD
	v_cvt_i32_f32_e32 v93, v93
	v_lshlrev_b32_e32 v91, 8, v91
	v_and_b32_e32 v91, 0xff00, v91
	v_and_b32_e32 v92, 0xff0000, v92
	v_perm_b32 v90, v93, v90, s81
	v_or3_b32 v90, v90, v91, v92
	v_mul_f32_e32 v92, v147, v95
	v_mul_f32_e32 v91, v147, v94
	v_rndne_f32_e32 v92, v92
	v_mul_f32_e32 v93, v147, v96
	v_mul_f32_e32 v94, v147, v97
	v_rndne_f32_e32 v91, v91
	v_cvt_i32_f32_e32 v92, v92
	v_rndne_f32_e32 v93, v93
	v_rndne_f32_e32 v94, v94
	v_cvt_i32_f32_e32 v91, v91
	v_cvt_i32_f32_sdwa v93, v93 dst_sel:WORD_1 dst_unused:UNUSED_PAD src0_sel:DWORD
	v_cvt_i32_f32_e32 v94, v94
	v_lshlrev_b32_e32 v92, 8, v92
	v_and_b32_e32 v92, 0xff00, v92
	v_and_b32_e32 v93, 0xff0000, v93
	v_perm_b32 v91, v94, v91, s81
	v_or3_b32 v91, v91, v92, v93
	v_mul_f32_e32 v93, v147, v99
	v_mul_f32_e32 v92, v147, v98
	v_rndne_f32_e32 v93, v93
	v_mul_f32_e32 v94, v147, v100
	v_mul_f32_e32 v95, v147, v101
	v_rndne_f32_e32 v92, v92
	v_cvt_i32_f32_e32 v93, v93
	v_rndne_f32_e32 v94, v94
	v_rndne_f32_e32 v95, v95
	v_cvt_i32_f32_e32 v92, v92
	v_cvt_i32_f32_sdwa v94, v94 dst_sel:WORD_1 dst_unused:UNUSED_PAD src0_sel:DWORD
	v_cvt_i32_f32_e32 v95, v95
	v_lshlrev_b32_e32 v93, 8, v93
	v_and_b32_e32 v93, 0xff00, v93
	v_and_b32_e32 v94, 0xff0000, v94
	v_perm_b32 v92, v95, v92, s81
	v_or3_b32 v92, v92, v93, v94
	v_mul_f32_e32 v94, v147, v103
	v_mul_f32_e32 v93, v147, v102
	v_rndne_f32_e32 v94, v94
	v_mul_f32_e32 v95, v147, v104
	v_mul_f32_e32 v96, v147, v105
	v_rndne_f32_e32 v93, v93
	v_cvt_i32_f32_e32 v94, v94
	v_rndne_f32_e32 v95, v95
	v_rndne_f32_e32 v96, v96
	v_cvt_i32_f32_e32 v93, v93
	v_cvt_i32_f32_sdwa v95, v95 dst_sel:WORD_1 dst_unused:UNUSED_PAD src0_sel:DWORD
	v_cvt_i32_f32_e32 v96, v96
	v_lshl_add_u64 v[80:81], s[50:51], 0, v[70:71]
	v_lshlrev_b32_e32 v94, 8, v94
	v_and_b32_e32 v94, 0xff00, v94
	v_and_b32_e32 v95, 0xff0000, v95
	v_perm_b32 v93, v96, v93, s81
	v_add_co_u32_e32 v80, vcc, s28, v80
	v_or3_b32 v93, v93, v94, v95
	s_nop 0
	v_addc_co_u32_e32 v81, vcc, 0, v81, vcc
	global_store_dwordx4 v[80:81], v[90:93], off
	v_mul_f32_e32 v94, v147, v113
	v_rndne_f32_e32 v94, v94
	v_mul_f32_e32 v91, v147, v107
	v_mul_f32_e32 v90, v147, v106
	v_rndne_f32_e32 v91, v91
	v_mul_f32_e32 v92, v147, v108
	v_mul_f32_e32 v93, v147, v109
	v_rndne_f32_e32 v90, v90
	v_cvt_i32_f32_e32 v91, v91
	v_rndne_f32_e32 v92, v92
	v_rndne_f32_e32 v93, v93
	v_cvt_i32_f32_e32 v90, v90
	v_cvt_i32_f32_sdwa v92, v92 dst_sel:WORD_1 dst_unused:UNUSED_PAD src0_sel:DWORD
	v_cvt_i32_f32_e32 v93, v93
	v_lshlrev_b32_e32 v91, 8, v91
	v_and_b32_e32 v91, 0xff00, v91
	v_and_b32_e32 v92, 0xff0000, v92
	v_perm_b32 v90, v93, v90, s81
	v_or3_b32 v90, v90, v91, v92
	v_mul_f32_e32 v92, v147, v111
	v_mul_f32_e32 v91, v147, v110
	v_rndne_f32_e32 v92, v92
	v_mul_f32_e32 v93, v147, v112
	v_rndne_f32_e32 v91, v91
	v_cvt_i32_f32_e32 v92, v92
	v_rndne_f32_e32 v93, v93
	v_cvt_i32_f32_e32 v91, v91
	v_cvt_i32_f32_sdwa v93, v93 dst_sel:WORD_1 dst_unused:UNUSED_PAD src0_sel:DWORD
	v_cvt_i32_f32_e32 v94, v94
	v_lshlrev_b32_e32 v92, 8, v92
	v_and_b32_e32 v92, 0xff00, v92
	v_and_b32_e32 v93, 0xff0000, v93
	v_perm_b32 v91, v94, v91, s81
	v_or3_b32 v91, v91, v92, v93
	v_mul_f32_e32 v93, v147, v115
	v_mul_f32_e32 v92, v147, v114
	v_rndne_f32_e32 v93, v93
	v_mul_f32_e32 v94, v147, v116
	v_mul_f32_e32 v95, v147, v117
	v_rndne_f32_e32 v92, v92
	v_cvt_i32_f32_e32 v93, v93
	v_rndne_f32_e32 v94, v94
	v_rndne_f32_e32 v95, v95
	v_cvt_i32_f32_e32 v92, v92
	v_cvt_i32_f32_sdwa v94, v94 dst_sel:WORD_1 dst_unused:UNUSED_PAD src0_sel:DWORD
	v_cvt_i32_f32_e32 v95, v95
	v_lshlrev_b32_e32 v93, 8, v93
	v_and_b32_e32 v93, 0xff00, v93
	v_and_b32_e32 v94, 0xff0000, v94
	v_perm_b32 v92, v95, v92, s81
	v_or3_b32 v92, v92, v93, v94
	v_mul_f32_e32 v94, v147, v119
	v_mul_f32_e32 v93, v147, v118
	v_rndne_f32_e32 v94, v94
	v_mul_f32_e32 v95, v147, v120
	v_mul_f32_e32 v96, v147, v121
	v_rndne_f32_e32 v93, v93
	v_cvt_i32_f32_e32 v94, v94
	v_rndne_f32_e32 v95, v95
	v_rndne_f32_e32 v96, v96
	v_cvt_i32_f32_e32 v93, v93
	v_cvt_i32_f32_sdwa v95, v95 dst_sel:WORD_1 dst_unused:UNUSED_PAD src0_sel:DWORD
	v_cvt_i32_f32_e32 v96, v96
	v_lshlrev_b32_e32 v94, 8, v94
	v_and_b32_e32 v94, 0xff00, v94
	v_and_b32_e32 v95, 0xff0000, v95
	v_perm_b32 v93, v96, v93, s81
	v_or3_b32 v93, v93, v94, v95
	global_store_dwordx4 v[80:81], v[90:93], off offset:1024
	v_mul_f32_e32 v94, v147, v129
	v_rndne_f32_e32 v94, v94
	v_mul_f32_e32 v91, v147, v123
	v_mul_f32_e32 v90, v147, v122
	v_rndne_f32_e32 v91, v91
	v_mul_f32_e32 v92, v147, v124
	v_mul_f32_e32 v93, v147, v125
	v_rndne_f32_e32 v90, v90
	v_cvt_i32_f32_e32 v91, v91
	v_rndne_f32_e32 v92, v92
	v_rndne_f32_e32 v93, v93
	v_cvt_i32_f32_e32 v90, v90
	v_cvt_i32_f32_sdwa v92, v92 dst_sel:WORD_1 dst_unused:UNUSED_PAD src0_sel:DWORD
	v_cvt_i32_f32_e32 v93, v93
	v_lshlrev_b32_e32 v91, 8, v91
	v_and_b32_e32 v91, 0xff00, v91
	v_and_b32_e32 v92, 0xff0000, v92
	v_perm_b32 v90, v93, v90, s81
	v_or3_b32 v90, v90, v91, v92
	v_mul_f32_e32 v92, v147, v127
	v_mul_f32_e32 v91, v147, v126
	v_rndne_f32_e32 v92, v92
	v_mul_f32_e32 v93, v147, v128
	v_rndne_f32_e32 v91, v91
	v_cvt_i32_f32_e32 v92, v92
	v_rndne_f32_e32 v93, v93
	v_cvt_i32_f32_e32 v91, v91
	v_cvt_i32_f32_sdwa v93, v93 dst_sel:WORD_1 dst_unused:UNUSED_PAD src0_sel:DWORD
	v_cvt_i32_f32_e32 v94, v94
	v_lshlrev_b32_e32 v92, 8, v92
	v_and_b32_e32 v92, 0xff00, v92
	v_and_b32_e32 v93, 0xff0000, v93
	v_perm_b32 v91, v94, v91, s81
	v_or3_b32 v91, v91, v92, v93
	v_mul_f32_e32 v93, v147, v131
	v_mul_f32_e32 v92, v147, v130
	v_rndne_f32_e32 v93, v93
	v_mul_f32_e32 v94, v147, v132
	v_mul_f32_e32 v95, v147, v133
	v_rndne_f32_e32 v92, v92
	v_cvt_i32_f32_e32 v93, v93
	v_rndne_f32_e32 v94, v94
	v_rndne_f32_e32 v95, v95
	v_cvt_i32_f32_e32 v92, v92
	v_cvt_i32_f32_sdwa v94, v94 dst_sel:WORD_1 dst_unused:UNUSED_PAD src0_sel:DWORD
	v_cvt_i32_f32_e32 v95, v95
	v_lshlrev_b32_e32 v93, 8, v93
	v_and_b32_e32 v93, 0xff00, v93
	v_and_b32_e32 v94, 0xff0000, v94
	v_perm_b32 v92, v95, v92, s81
	v_or3_b32 v92, v92, v93, v94
	v_mul_f32_e32 v94, v147, v135
	v_mul_f32_e32 v93, v147, v134
	v_rndne_f32_e32 v94, v94
	v_mul_f32_e32 v95, v147, v136
	v_mul_f32_e32 v96, v147, v137
	v_rndne_f32_e32 v93, v93
	v_cvt_i32_f32_e32 v94, v94
	v_rndne_f32_e32 v95, v95
	v_rndne_f32_e32 v96, v96
	v_cvt_i32_f32_e32 v93, v93
	v_cvt_i32_f32_sdwa v95, v95 dst_sel:WORD_1 dst_unused:UNUSED_PAD src0_sel:DWORD
	v_cvt_i32_f32_e32 v96, v96
	v_lshlrev_b32_e32 v94, 8, v94
	v_and_b32_e32 v94, 0xff00, v94
	v_and_b32_e32 v95, 0xff0000, v95
	v_perm_b32 v93, v96, v93, s81
	v_or3_b32 v93, v93, v94, v95
	global_store_dwordx4 v[80:81], v[90:93], off offset:2048
	v_mul_f32_e32 v94, v147, v145
	v_rndne_f32_e32 v94, v94
	v_mul_f32_e32 v91, v147, v139
	v_mul_f32_e32 v90, v147, v138
	v_rndne_f32_e32 v91, v91
	v_mul_f32_e32 v92, v147, v140
	v_mul_f32_e32 v93, v147, v141
	v_rndne_f32_e32 v90, v90
	v_cvt_i32_f32_e32 v91, v91
	v_rndne_f32_e32 v92, v92
	v_rndne_f32_e32 v93, v93
	v_cvt_i32_f32_e32 v90, v90
	v_cvt_i32_f32_sdwa v92, v92 dst_sel:WORD_1 dst_unused:UNUSED_PAD src0_sel:DWORD
	v_cvt_i32_f32_e32 v93, v93
	v_lshlrev_b32_e32 v91, 8, v91
	v_and_b32_e32 v91, 0xff00, v91
	v_and_b32_e32 v92, 0xff0000, v92
	v_perm_b32 v90, v93, v90, s81
	v_or3_b32 v90, v90, v91, v92
	v_mul_f32_e32 v92, v147, v143
	v_mul_f32_e32 v91, v147, v142
	v_rndne_f32_e32 v92, v92
	v_mul_f32_e32 v93, v147, v144
	v_rndne_f32_e32 v91, v91
	v_cvt_i32_f32_e32 v92, v92
	v_rndne_f32_e32 v93, v93
	v_cvt_i32_f32_e32 v91, v91
	v_cvt_i32_f32_sdwa v93, v93 dst_sel:WORD_1 dst_unused:UNUSED_PAD src0_sel:DWORD
	v_cvt_i32_f32_e32 v94, v94
	v_lshlrev_b32_e32 v92, 8, v92
	v_and_b32_e32 v92, 0xff00, v92
	v_and_b32_e32 v93, 0xff0000, v93
	v_perm_b32 v91, v94, v91, s81
	v_mul_f32_e32 v86, v147, v86
	v_mul_f32_e32 v82, v147, v82
	v_or3_b32 v91, v91, v92, v93
	v_mul_f32_e32 v92, v147, v146
	v_rndne_f32_e32 v86, v86
	v_mul_f32_e32 v85, v147, v85
	v_mul_f32_e32 v84, v147, v84
	v_mul_f32_e32 v83, v147, v83
	v_rndne_f32_e32 v82, v82
	v_mul_f32_e32 v35, v147, v35
	v_mul_f32_e32 v0, v147, v0
	v_rndne_f32_e32 v92, v92
	v_cvt_i32_f32_e32 v86, v86
	v_rndne_f32_e32 v85, v85
	v_rndne_f32_e32 v84, v84
	v_rndne_f32_e32 v83, v83
	v_cvt_i32_f32_e32 v82, v82
	v_rndne_f32_e32 v35, v35
	v_rndne_f32_e32 v0, v0
	v_cvt_i32_f32_e32 v92, v92
	v_cvt_i32_f32_sdwa v85, v85 dst_sel:WORD_1 dst_unused:UNUSED_PAD src0_sel:DWORD
	v_cvt_i32_f32_e32 v84, v84
	v_cvt_i32_f32_e32 v83, v83
	v_cvt_i32_f32_sdwa v35, v35 dst_sel:WORD_1 dst_unused:UNUSED_PAD src0_sel:DWORD
	v_cvt_i32_f32_e32 v0, v0
	v_lshlrev_b32_e32 v86, 8, v86
	v_lshlrev_b32_e32 v82, 8, v82
	v_and_b32_e32 v86, 0xff00, v86
	v_and_b32_e32 v85, 0xff0000, v85
	v_perm_b32 v84, v84, v92, s81
	v_and_b32_e32 v82, 0xff00, v82
	v_and_b32_e32 v35, 0xff0000, v35
	v_perm_b32 v0, v0, v83, s81
	v_or3_b32 v92, v84, v86, v85
	v_or3_b32 v93, v0, v82, v35
	global_store_dwordx4 v[80:81], v[90:93], off offset:3072
	s_and_saveexec_b64 s[60:61], s[10:11]
	s_cbranch_execnz .LBB0_996
	s_or_b64 exec, exec, s[60:61]
	s_andn2_b64 vcc, exec, s[52:53]
	s_mov_b64 s[52:53], -1
	s_cbranch_vccnz .LBB0_991
	s_branch .LBB0_997

.LBB0_999:
	v_and_b32_e32 v91, 0xffff0000, v40
	v_lshlrev_b32_e32 v90, 16, v40
	v_mul_f32_e32 v87, v91, v91
	v_lshlrev_b32_e32 v92, 16, v41
	v_fmac_f32_e32 v87, v90, v90
	v_and_b32_e32 v93, 0xffff0000, v41
	v_fmac_f32_e32 v87, v92, v92
	v_lshlrev_b32_e32 v94, 16, v42
	v_fmac_f32_e32 v87, v93, v93
	v_and_b32_e32 v95, 0xffff0000, v42
	v_fmac_f32_e32 v87, v94, v94
	v_lshlrev_b32_e32 v96, 16, v43
	v_fmac_f32_e32 v87, v95, v95
	v_and_b32_e32 v97, 0xffff0000, v43
	v_fmac_f32_e32 v87, v96, v96
	v_lshlrev_b32_e32 v98, 16, v36
	v_fmac_f32_e32 v87, v97, v97
	v_and_b32_e32 v99, 0xffff0000, v36
	v_fmac_f32_e32 v87, v98, v98
	v_lshlrev_b32_e32 v100, 16, v37
	v_fmac_f32_e32 v87, v99, v99
	v_and_b32_e32 v101, 0xffff0000, v37
	v_fmac_f32_e32 v87, v100, v100
	v_lshlrev_b32_e32 v102, 16, v38
	v_fmac_f32_e32 v87, v101, v101
	v_and_b32_e32 v103, 0xffff0000, v38
	v_fmac_f32_e32 v87, v102, v102
	v_lshlrev_b32_e32 v104, 16, v39
	v_fmac_f32_e32 v87, v103, v103
	v_and_b32_e32 v105, 0xffff0000, v39
	v_fmac_f32_e32 v87, v104, v104
	v_lshlrev_b32_e32 v106, 16, v48
	v_fmac_f32_e32 v87, v105, v105
	v_and_b32_e32 v107, 0xffff0000, v48
	v_fmac_f32_e32 v87, v106, v106
	v_lshlrev_b32_e32 v108, 16, v49
	v_fmac_f32_e32 v87, v107, v107
	v_and_b32_e32 v109, 0xffff0000, v49
	v_fmac_f32_e32 v87, v108, v108
	v_lshlrev_b32_e32 v110, 16, v50
	v_fmac_f32_e32 v87, v109, v109
	v_and_b32_e32 v111, 0xffff0000, v50
	v_fmac_f32_e32 v87, v110, v110
	v_lshlrev_b32_e32 v112, 16, v51
	v_fmac_f32_e32 v87, v111, v111
	v_and_b32_e32 v113, 0xffff0000, v51
	v_fmac_f32_e32 v87, v112, v112
	v_max3_f32 v0, |v90|, 0, |v91|
	v_lshlrev_b32_e32 v114, 16, v44
	v_fmac_f32_e32 v87, v113, v113
	v_max3_f32 v0, v0, |v92|, |v93|
	v_and_b32_e32 v115, 0xffff0000, v44
	v_fmac_f32_e32 v87, v114, v114
	v_max3_f32 v0, v0, |v94|, |v95|
	v_lshlrev_b32_e32 v116, 16, v45
	v_fmac_f32_e32 v87, v115, v115
	v_max3_f32 v0, v0, |v96|, |v97|
	v_and_b32_e32 v117, 0xffff0000, v45
	v_fmac_f32_e32 v87, v116, v116
	v_max3_f32 v0, v0, |v98|, |v99|
	v_lshlrev_b32_e32 v118, 16, v46
	v_fmac_f32_e32 v87, v117, v117
	v_max3_f32 v0, v0, |v100|, |v101|
	v_and_b32_e32 v119, 0xffff0000, v46
	v_fmac_f32_e32 v87, v118, v118
	v_max3_f32 v0, v0, |v102|, |v103|
	v_lshlrev_b32_e32 v120, 16, v47
	v_fmac_f32_e32 v87, v119, v119
	v_max3_f32 v0, v0, |v104|, |v105|
	v_and_b32_e32 v121, 0xffff0000, v47
	v_fmac_f32_e32 v87, v120, v120
	v_max3_f32 v0, v0, |v106|, |v107|
	v_lshlrev_b32_e32 v122, 16, v56
	v_fmac_f32_e32 v87, v121, v121
	v_max3_f32 v0, v0, |v108|, |v109|
	v_and_b32_e32 v123, 0xffff0000, v56
	v_fmac_f32_e32 v87, v122, v122
	v_max3_f32 v0, v0, |v110|, |v111|
	v_lshlrev_b32_e32 v124, 16, v57
	v_fmac_f32_e32 v87, v123, v123
	v_max3_f32 v0, v0, |v112|, |v113|
	v_and_b32_e32 v125, 0xffff0000, v57
	v_fmac_f32_e32 v87, v124, v124
	v_max3_f32 v0, v0, |v114|, |v115|
	v_lshlrev_b32_e32 v126, 16, v58
	v_fmac_f32_e32 v87, v125, v125
	v_max3_f32 v0, v0, |v116|, |v117|
	v_and_b32_e32 v127, 0xffff0000, v58
	v_fmac_f32_e32 v87, v126, v126
	v_max3_f32 v0, v0, |v118|, |v119|
	v_lshlrev_b32_e32 v128, 16, v59
	v_fmac_f32_e32 v87, v127, v127
	v_max3_f32 v0, v0, |v120|, |v121|
	v_and_b32_e32 v129, 0xffff0000, v59
	v_fmac_f32_e32 v87, v128, v128
	v_lshlrev_b32_e32 v130, 16, v52
	v_max3_f32 v0, v0, |v122|, |v123|
	v_fmac_f32_e32 v87, v129, v129
	v_and_b32_e32 v131, 0xffff0000, v52
	v_max3_f32 v0, v0, |v124|, |v125|
	v_fmac_f32_e32 v87, v130, v130
	v_lshlrev_b32_e32 v132, 16, v53
	v_max3_f32 v0, v0, |v126|, |v127|
	v_fmac_f32_e32 v87, v131, v131
	v_and_b32_e32 v133, 0xffff0000, v53
	v_max3_f32 v0, v0, |v128|, |v129|
	v_fmac_f32_e32 v87, v132, v132
	v_lshlrev_b32_e32 v134, 16, v54
	v_max3_f32 v0, v0, |v130|, |v131|
	v_fmac_f32_e32 v87, v133, v133
	v_and_b32_e32 v135, 0xffff0000, v54
	v_max3_f32 v0, v0, |v132|, |v133|
	v_fmac_f32_e32 v87, v134, v134
	v_lshlrev_b32_e32 v136, 16, v55
	v_and_b32_e32 v137, 0xffff0000, v55
	v_max3_f32 v0, v0, |v134|, |v135|
	v_fmac_f32_e32 v87, v135, v135
	v_max3_f32 v80, v0, |v136|, |v137|
	v_lshlrev_b32_e32 v138, 16, v64
	v_and_b32_e32 v139, 0xffff0000, v64
	v_fmac_f32_e32 v87, v136, v136
	v_lshlrev_b32_e32 v140, 16, v65
	v_and_b32_e32 v141, 0xffff0000, v65
	v_max3_f32 v80, v80, |v138|, |v139|
	v_fmac_f32_e32 v87, v137, v137
	v_lshlrev_b32_e32 v142, 16, v66
	v_and_b32_e32 v143, 0xffff0000, v66
	v_max3_f32 v80, v80, |v140|, |v141|
	v_fmac_f32_e32 v87, v138, v138
	v_lshlrev_b32_e32 v144, 16, v67
	v_and_b32_e32 v145, 0xffff0000, v67
	v_max3_f32 v80, v80, |v142|, |v143|
	v_fmac_f32_e32 v87, v139, v139
	v_lshlrev_b32_e32 v146, 16, v60
	v_and_b32_e32 v86, 0xffff0000, v60
	v_max3_f32 v80, v80, |v144|, |v145|
	v_fmac_f32_e32 v87, v140, v140
	v_lshlrev_b32_e32 v85, 16, v61
	v_and_b32_e32 v84, 0xffff0000, v61
	v_max3_f32 v80, v80, |v146|, |v86|
	v_fmac_f32_e32 v87, v141, v141
	v_lshlrev_b32_e32 v83, 16, v62
	v_and_b32_e32 v82, 0xffff0000, v62
	v_max3_f32 v80, v80, |v85|, |v84|
	v_fmac_f32_e32 v87, v142, v142
	v_lshlrev_b32_e32 v35, 16, v63
	v_and_b32_e32 v0, 0xffff0000, v63
	v_max3_f32 v80, v80, |v83|, |v82|
	v_fmac_f32_e32 v87, v143, v143
	v_max3_f32 v80, v80, |v35|, |v0|
	v_fmac_f32_e32 v87, v144, v144
	s_nop 1
	v_mov_b32_dpp v81, v80 quad_perm:[1,0,3,2] row_mask:0xf bank_mask:0xf
	v_fmac_f32_e32 v87, v145, v145
	v_fmac_f32_e32 v87, v146, v146
	v_fmac_f32_e32 v87, v86, v86
	v_fmac_f32_e32 v87, v85, v85
	v_fmac_f32_e32 v87, v84, v84
	s_waitcnt lgkmcnt(0)
	v_max_f32_e32 v81, v81, v81
	v_fmac_f32_e32 v87, v83, v83
	v_max_f32_e32 v80, v80, v81
	v_fmac_f32_e32 v87, v82, v82
	s_nop 1
	v_mov_b32_dpp v81, v80 quad_perm:[2,3,0,1] row_mask:0xf bank_mask:0xf
	v_fmac_f32_e32 v87, v35, v35
	v_fmac_f32_e32 v87, v0, v0
	s_nop 1
	v_mov_b32_dpp v88, v87 quad_perm:[1,0,3,2] row_mask:0xf bank_mask:0xf
	s_waitcnt lgkmcnt(0)
	v_max_f32_e32 v81, v81, v81
	v_max_f32_e32 v80, v80, v81
	s_nop 1
	v_mov_b32_dpp v81, v80 row_shl:4 row_mask:0xf bank_mask:0x5
	v_mov_b32_dpp v81, v80 row_shr:4 row_mask:0xf bank_mask:0xa
	s_waitcnt lgkmcnt(0)
	v_add_f32_e32 v87, v87, v88
	s_nop 1
	v_mov_b32_dpp v88, v87 quad_perm:[2,3,0,1] row_mask:0xf bank_mask:0xf
	s_waitcnt lgkmcnt(0)
	v_max_f32_e32 v81, v81, v81
	v_max_f32_e32 v80, v80, v81
	s_waitcnt lgkmcnt(0)
	v_add_f32_e32 v87, v87, v88
	s_nop 1
	v_mov_b32_dpp v81, v80 row_ror:8 row_mask:0xf bank_mask:0xf
	s_nop 1
	v_mov_b32_dpp v88, v87 row_shl:4 row_mask:0xf bank_mask:0x5
	v_mov_b32_dpp v88, v87 row_shr:4 row_mask:0xf bank_mask:0xa
	s_waitcnt lgkmcnt(0)
	v_max_f32_e32 v81, v81, v81
	s_waitcnt lgkmcnt(0)
	v_add_f32_e32 v87, v87, v88
	v_max_f32_e32 v80, v80, v81
	s_nop 1
	v_mov_b32_dpp v88, v87 row_ror:8 row_mask:0xf bank_mask:0xf
	ds_swizzle_b32 v81, v80 offset:swizzle(SWAP,16)
	s_waitcnt lgkmcnt(0)
	v_add_f32_e32 v87, v87, v88
	s_waitcnt lgkmcnt(0)
	v_max_f32_e32 v81, v81, v81
	ds_swizzle_b32 v88, v87 offset:swizzle(SWAP,16)
	v_max_f32_e32 v80, v80, v81
	v_mov_b32_e32 v81, v80
	s_nop 1
	v_permlane32_swap_b32_e32 v80, v81
	v_max_f32_e32 v81, v81, v81
	v_max_f32_e32 v80, v80, v80
	s_waitcnt lgkmcnt(0)
	v_add_f32_e32 v88, v87, v88
	v_max_f32_e32 v87, v80, v81
	v_div_scale_f32 v80, s[12:13], v87, v87, s79
	v_rcp_f32_e32 v81, v80
	v_mov_b32_e32 v89, v88
	s_nop 1
	v_permlane32_swap_b32_e32 v88, v89
	v_fma_f32 v147, -v80, v81, 1.0
	v_fmac_f32_e32 v81, v147, v81
	v_div_scale_f32 v147, vcc, s79, v87, s79
	v_mul_f32_e32 v148, v147, v81
	v_fma_f32 v149, -v80, v148, v147
	v_fmac_f32_e32 v148, v149, v81
	v_fma_f32 v80, -v80, v148, v147
	v_div_fmas_f32 v80, v80, v81, v148
	v_div_fixup_f32 v80, v80, v87, s79
	v_cmp_lt_f32_e32 vcc, 0, v87
	s_nop 1
	v_cndmask_b32_e32 v147, 0, v80, vcc
	v_mul_f32_e32 v91, v147, v91
	v_mul_f32_e32 v90, v147, v90
	v_rndne_f32_e32 v91, v91
	v_mul_f32_e32 v92, v147, v92
	v_mul_f32_e32 v93, v147, v93
	v_rndne_f32_e32 v90, v90
	v_cvt_i32_f32_e32 v91, v91
	v_rndne_f32_e32 v92, v92
	v_rndne_f32_e32 v93, v93
	v_cvt_i32_f32_e32 v90, v90
	v_cvt_i32_f32_sdwa v92, v92 dst_sel:WORD_1 dst_unused:UNUSED_PAD src0_sel:DWORD
	v_cvt_i32_f32_e32 v93, v93
	v_lshlrev_b32_e32 v91, 8, v91
	v_and_b32_e32 v91, 0xff00, v91
	v_and_b32_e32 v92, 0xff0000, v92
	v_perm_b32 v90, v93, v90, s81
	v_or3_b32 v90, v90, v91, v92
	v_mul_f32_e32 v92, v147, v95
	v_mul_f32_e32 v91, v147, v94
	v_rndne_f32_e32 v92, v92
	v_mul_f32_e32 v93, v147, v96
	v_mul_f32_e32 v94, v147, v97
	v_rndne_f32_e32 v91, v91
	v_cvt_i32_f32_e32 v92, v92
	v_rndne_f32_e32 v93, v93
	v_rndne_f32_e32 v94, v94
	v_cvt_i32_f32_e32 v91, v91
	v_cvt_i32_f32_sdwa v93, v93 dst_sel:WORD_1 dst_unused:UNUSED_PAD src0_sel:DWORD
	v_cvt_i32_f32_e32 v94, v94
	v_lshlrev_b32_e32 v92, 8, v92
	v_and_b32_e32 v92, 0xff00, v92
	v_and_b32_e32 v93, 0xff0000, v93
	v_perm_b32 v91, v94, v91, s81
	v_or3_b32 v91, v91, v92, v93
	v_mul_f32_e32 v93, v147, v99
	v_mul_f32_e32 v92, v147, v98
	v_rndne_f32_e32 v93, v93
	v_mul_f32_e32 v94, v147, v100
	v_mul_f32_e32 v95, v147, v101
	v_rndne_f32_e32 v92, v92
	v_cvt_i32_f32_e32 v93, v93
	v_rndne_f32_e32 v94, v94
	v_rndne_f32_e32 v95, v95
	v_cvt_i32_f32_e32 v92, v92
	v_cvt_i32_f32_sdwa v94, v94 dst_sel:WORD_1 dst_unused:UNUSED_PAD src0_sel:DWORD
	v_cvt_i32_f32_e32 v95, v95
	v_lshlrev_b32_e32 v93, 8, v93
	v_and_b32_e32 v93, 0xff00, v93
	v_and_b32_e32 v94, 0xff0000, v94
	v_perm_b32 v92, v95, v92, s81
	v_or3_b32 v92, v92, v93, v94
	v_mul_f32_e32 v94, v147, v103
	v_mul_f32_e32 v93, v147, v102
	v_rndne_f32_e32 v94, v94
	v_mul_f32_e32 v95, v147, v104
	v_mul_f32_e32 v96, v147, v105
	v_rndne_f32_e32 v93, v93
	v_cvt_i32_f32_e32 v94, v94
	v_rndne_f32_e32 v95, v95
	v_rndne_f32_e32 v96, v96
	v_cvt_i32_f32_e32 v93, v93
	v_cvt_i32_f32_sdwa v95, v95 dst_sel:WORD_1 dst_unused:UNUSED_PAD src0_sel:DWORD
	v_cvt_i32_f32_e32 v96, v96
	v_lshl_add_u64 v[80:81], s[50:51], 0, v[72:73]
	v_lshlrev_b32_e32 v94, 8, v94
	v_and_b32_e32 v94, 0xff00, v94
	v_and_b32_e32 v95, 0xff0000, v95
	v_perm_b32 v93, v96, v93, s81
	v_add_co_u32_e32 v80, vcc, s28, v80
	v_or3_b32 v93, v93, v94, v95
	s_nop 0
	v_addc_co_u32_e32 v81, vcc, 0, v81, vcc
	global_store_dwordx4 v[80:81], v[90:93], off
	v_mul_f32_e32 v94, v147, v113
	v_rndne_f32_e32 v94, v94
	v_mul_f32_e32 v91, v147, v107
	v_mul_f32_e32 v90, v147, v106
	v_rndne_f32_e32 v91, v91
	v_mul_f32_e32 v92, v147, v108
	v_mul_f32_e32 v93, v147, v109
	v_rndne_f32_e32 v90, v90
	v_cvt_i32_f32_e32 v91, v91
	v_rndne_f32_e32 v92, v92
	v_rndne_f32_e32 v93, v93
	v_cvt_i32_f32_e32 v90, v90
	v_cvt_i32_f32_sdwa v92, v92 dst_sel:WORD_1 dst_unused:UNUSED_PAD src0_sel:DWORD
	v_cvt_i32_f32_e32 v93, v93
	v_lshlrev_b32_e32 v91, 8, v91
	v_and_b32_e32 v91, 0xff00, v91
	v_and_b32_e32 v92, 0xff0000, v92
	v_perm_b32 v90, v93, v90, s81
	v_or3_b32 v90, v90, v91, v92
	v_mul_f32_e32 v92, v147, v111
	v_mul_f32_e32 v91, v147, v110
	v_rndne_f32_e32 v92, v92
	v_mul_f32_e32 v93, v147, v112
	v_rndne_f32_e32 v91, v91
	v_cvt_i32_f32_e32 v92, v92
	v_rndne_f32_e32 v93, v93
	v_cvt_i32_f32_e32 v91, v91
	v_cvt_i32_f32_sdwa v93, v93 dst_sel:WORD_1 dst_unused:UNUSED_PAD src0_sel:DWORD
	v_cvt_i32_f32_e32 v94, v94
	v_lshlrev_b32_e32 v92, 8, v92
	v_and_b32_e32 v92, 0xff00, v92
	v_and_b32_e32 v93, 0xff0000, v93
	v_perm_b32 v91, v94, v91, s81
	v_or3_b32 v91, v91, v92, v93
	v_mul_f32_e32 v93, v147, v115
	v_mul_f32_e32 v92, v147, v114
	v_rndne_f32_e32 v93, v93
	v_mul_f32_e32 v94, v147, v116
	v_mul_f32_e32 v95, v147, v117
	v_rndne_f32_e32 v92, v92
	v_cvt_i32_f32_e32 v93, v93
	v_rndne_f32_e32 v94, v94
	v_rndne_f32_e32 v95, v95
	v_cvt_i32_f32_e32 v92, v92
	v_cvt_i32_f32_sdwa v94, v94 dst_sel:WORD_1 dst_unused:UNUSED_PAD src0_sel:DWORD
	v_cvt_i32_f32_e32 v95, v95
	v_lshlrev_b32_e32 v93, 8, v93
	v_and_b32_e32 v93, 0xff00, v93
	v_and_b32_e32 v94, 0xff0000, v94
	v_perm_b32 v92, v95, v92, s81
	v_or3_b32 v92, v92, v93, v94
	v_mul_f32_e32 v94, v147, v119
	v_mul_f32_e32 v93, v147, v118
	v_rndne_f32_e32 v94, v94
	v_mul_f32_e32 v95, v147, v120
	v_mul_f32_e32 v96, v147, v121
	v_rndne_f32_e32 v93, v93
	v_cvt_i32_f32_e32 v94, v94
	v_rndne_f32_e32 v95, v95
	v_rndne_f32_e32 v96, v96
	v_cvt_i32_f32_e32 v93, v93
	v_cvt_i32_f32_sdwa v95, v95 dst_sel:WORD_1 dst_unused:UNUSED_PAD src0_sel:DWORD
	v_cvt_i32_f32_e32 v96, v96
	v_lshlrev_b32_e32 v94, 8, v94
	v_and_b32_e32 v94, 0xff00, v94
	v_and_b32_e32 v95, 0xff0000, v95
	v_perm_b32 v93, v96, v93, s81
	v_or3_b32 v93, v93, v94, v95
	global_store_dwordx4 v[80:81], v[90:93], off offset:1024
	v_mul_f32_e32 v94, v147, v129
	v_rndne_f32_e32 v94, v94
	v_mul_f32_e32 v91, v147, v123
	v_mul_f32_e32 v90, v147, v122
	v_rndne_f32_e32 v91, v91
	v_mul_f32_e32 v92, v147, v124
	v_mul_f32_e32 v93, v147, v125
	v_rndne_f32_e32 v90, v90
	v_cvt_i32_f32_e32 v91, v91
	v_rndne_f32_e32 v92, v92
	v_rndne_f32_e32 v93, v93
	v_cvt_i32_f32_e32 v90, v90
	v_cvt_i32_f32_sdwa v92, v92 dst_sel:WORD_1 dst_unused:UNUSED_PAD src0_sel:DWORD
	v_cvt_i32_f32_e32 v93, v93
	v_lshlrev_b32_e32 v91, 8, v91
	v_and_b32_e32 v91, 0xff00, v91
	v_and_b32_e32 v92, 0xff0000, v92
	v_perm_b32 v90, v93, v90, s81
	v_or3_b32 v90, v90, v91, v92
	v_mul_f32_e32 v92, v147, v127
	v_mul_f32_e32 v91, v147, v126
	v_rndne_f32_e32 v92, v92
	v_mul_f32_e32 v93, v147, v128
	v_rndne_f32_e32 v91, v91
	v_cvt_i32_f32_e32 v92, v92
	v_rndne_f32_e32 v93, v93
	v_cvt_i32_f32_e32 v91, v91
	v_cvt_i32_f32_sdwa v93, v93 dst_sel:WORD_1 dst_unused:UNUSED_PAD src0_sel:DWORD
	v_cvt_i32_f32_e32 v94, v94
	v_lshlrev_b32_e32 v92, 8, v92
	v_and_b32_e32 v92, 0xff00, v92
	v_and_b32_e32 v93, 0xff0000, v93
	v_perm_b32 v91, v94, v91, s81
	v_or3_b32 v91, v91, v92, v93
	v_mul_f32_e32 v93, v147, v131
	v_mul_f32_e32 v92, v147, v130
	v_rndne_f32_e32 v93, v93
	v_mul_f32_e32 v94, v147, v132
	v_mul_f32_e32 v95, v147, v133
	v_rndne_f32_e32 v92, v92
	v_cvt_i32_f32_e32 v93, v93
	v_rndne_f32_e32 v94, v94
	v_rndne_f32_e32 v95, v95
	v_cvt_i32_f32_e32 v92, v92
	v_cvt_i32_f32_sdwa v94, v94 dst_sel:WORD_1 dst_unused:UNUSED_PAD src0_sel:DWORD
	v_cvt_i32_f32_e32 v95, v95
	v_lshlrev_b32_e32 v93, 8, v93
	v_and_b32_e32 v93, 0xff00, v93
	v_and_b32_e32 v94, 0xff0000, v94
	v_perm_b32 v92, v95, v92, s81
	v_or3_b32 v92, v92, v93, v94
	v_mul_f32_e32 v94, v147, v135
	v_mul_f32_e32 v93, v147, v134
	v_rndne_f32_e32 v94, v94
	v_mul_f32_e32 v95, v147, v136
	v_mul_f32_e32 v96, v147, v137
	v_rndne_f32_e32 v93, v93
	v_cvt_i32_f32_e32 v94, v94
	v_rndne_f32_e32 v95, v95
	v_rndne_f32_e32 v96, v96
	v_cvt_i32_f32_e32 v93, v93
	v_cvt_i32_f32_sdwa v95, v95 dst_sel:WORD_1 dst_unused:UNUSED_PAD src0_sel:DWORD
	v_cvt_i32_f32_e32 v96, v96
	v_lshlrev_b32_e32 v94, 8, v94
	v_and_b32_e32 v94, 0xff00, v94
	v_and_b32_e32 v95, 0xff0000, v95
	v_perm_b32 v93, v96, v93, s81
	v_or3_b32 v93, v93, v94, v95
	global_store_dwordx4 v[80:81], v[90:93], off offset:2048
	v_mul_f32_e32 v94, v147, v145
	v_rndne_f32_e32 v94, v94
	v_mul_f32_e32 v91, v147, v139
	v_mul_f32_e32 v90, v147, v138
	v_rndne_f32_e32 v91, v91
	v_mul_f32_e32 v92, v147, v140
	v_mul_f32_e32 v93, v147, v141
	v_rndne_f32_e32 v90, v90
	v_cvt_i32_f32_e32 v91, v91
	v_rndne_f32_e32 v92, v92
	v_rndne_f32_e32 v93, v93
	v_cvt_i32_f32_e32 v90, v90
	v_cvt_i32_f32_sdwa v92, v92 dst_sel:WORD_1 dst_unused:UNUSED_PAD src0_sel:DWORD
	v_cvt_i32_f32_e32 v93, v93
	v_lshlrev_b32_e32 v91, 8, v91
	v_and_b32_e32 v91, 0xff00, v91
	v_and_b32_e32 v92, 0xff0000, v92
	v_perm_b32 v90, v93, v90, s81
	v_or3_b32 v90, v90, v91, v92
	v_mul_f32_e32 v92, v147, v143
	v_mul_f32_e32 v91, v147, v142
	v_rndne_f32_e32 v92, v92
	v_mul_f32_e32 v93, v147, v144
	v_rndne_f32_e32 v91, v91
	v_cvt_i32_f32_e32 v92, v92
	v_rndne_f32_e32 v93, v93
	v_cvt_i32_f32_e32 v91, v91
	v_cvt_i32_f32_sdwa v93, v93 dst_sel:WORD_1 dst_unused:UNUSED_PAD src0_sel:DWORD
	v_cvt_i32_f32_e32 v94, v94
	v_lshlrev_b32_e32 v92, 8, v92
	v_and_b32_e32 v92, 0xff00, v92
	v_and_b32_e32 v93, 0xff0000, v93
	v_perm_b32 v91, v94, v91, s81
	v_mul_f32_e32 v86, v147, v86
	v_mul_f32_e32 v82, v147, v82
	v_or3_b32 v91, v91, v92, v93
	v_mul_f32_e32 v92, v147, v146
	v_rndne_f32_e32 v86, v86
	v_mul_f32_e32 v85, v147, v85
	v_mul_f32_e32 v84, v147, v84
	v_mul_f32_e32 v83, v147, v83
	v_rndne_f32_e32 v82, v82
	v_mul_f32_e32 v35, v147, v35
	v_mul_f32_e32 v0, v147, v0
	v_rndne_f32_e32 v92, v92
	v_cvt_i32_f32_e32 v86, v86
	v_rndne_f32_e32 v85, v85
	v_rndne_f32_e32 v84, v84
	v_rndne_f32_e32 v83, v83
	v_cvt_i32_f32_e32 v82, v82
	v_rndne_f32_e32 v35, v35
	v_rndne_f32_e32 v0, v0
	v_cvt_i32_f32_e32 v92, v92
	v_cvt_i32_f32_sdwa v85, v85 dst_sel:WORD_1 dst_unused:UNUSED_PAD src0_sel:DWORD
	v_cvt_i32_f32_e32 v84, v84
	v_cvt_i32_f32_e32 v83, v83
	v_cvt_i32_f32_sdwa v35, v35 dst_sel:WORD_1 dst_unused:UNUSED_PAD src0_sel:DWORD
	v_cvt_i32_f32_e32 v0, v0
	v_lshlrev_b32_e32 v86, 8, v86
	v_lshlrev_b32_e32 v82, 8, v82
	v_and_b32_e32 v86, 0xff00, v86
	v_and_b32_e32 v85, 0xff0000, v85
	v_perm_b32 v84, v84, v92, s81
	v_and_b32_e32 v82, 0xff00, v82
	v_and_b32_e32 v35, 0xff0000, v35
	v_perm_b32 v0, v0, v83, s81
	v_or3_b32 v92, v84, v86, v85
	v_or3_b32 v93, v0, v82, v35
	global_store_dwordx4 v[80:81], v[90:93], off offset:3072
	s_and_saveexec_b64 s[60:61], s[10:11]
	s_cbranch_execz .LBB0_990
	v_add_f32_e32 v0, v88, v89
	v_fmamk_f32 v0, v0, 0x39800000, v214
	v_mul_f32_e32 v35, 0x4f800000, v0
	v_cmp_gt_f32_e32 vcc, s54, v0
	s_nop 1
	v_cndmask_b32_e32 v0, v0, v35, vcc
	v_sqrt_f32_e32 v35, v0
	s_nop 0
	v_add_u32_e32 v80, -1, v35
	v_fma_f32 v82, -v80, v35, v0
	v_add_u32_e32 v81, 1, v35
	v_cmp_ge_f32_e64 s[12:13], 0, v82
	s_nop 1
	v_cndmask_b32_e64 v80, v35, v80, s[12:13]
	v_fma_f32 v35, -v81, v35, v0
	v_cmp_lt_f32_e64 s[12:13], 0, v35
	s_nop 1
	v_cndmask_b32_e64 v35, v80, v81, s[12:13]
	v_mul_f32_e32 v80, 0x37800000, v35
	v_cndmask_b32_e32 v35, v35, v80, vcc
	v_cmp_class_f32_e32 vcc, v0, v252
	v_mul_f32_e32 v81, 0x3c010204, v87
	s_nop 0
	v_cndmask_b32_e32 v0, v35, v0, vcc
	v_div_scale_f32 v35, s[12:13], v0, v0, 1.0
	v_rcp_f32_e32 v80, v35
	s_nop 0
	v_fma_f32 v82, -v35, v80, 1.0
	v_fmac_f32_e32 v80, v82, v80
	v_div_scale_f32 v82, vcc, 1.0, v0, 1.0
	v_mul_f32_e32 v83, v82, v80
	v_fma_f32 v84, -v35, v83, v82
	v_fmac_f32_e32 v83, v84, v80
	v_fma_f32 v35, -v35, v83, v82
	v_div_fmas_f32 v35, v35, v80, v83
	v_div_fixup_f32 v0, v35, v0, 1.0
	v_mul_f32_e32 v0, v81, v0
	v_lshl_add_u64 v[80:81], s[50:51], 0, v[76:77]
	global_store_dword v[80:81], v0, off
	s_branch .LBB0_990

.LBB0_1363:
	v_mov_b32_e32 v4, v22
	s_add_u32 s6, s12, s14
	s_addc_u32 s7, s13, s15
	v_ashrrev_i32_e32 v5, 31, v4
	v_lshl_add_u64 v[2:3], v[4:5], 4, s[6:7]
	s_add_u32 s6, s12, s16
	s_addc_u32 s7, s13, s17
	v_lshlrev_b32_e32 v6, 1, v4
	v_lshl_add_u64 v[4:5], v[4:5], 2, s[6:7]
	global_load_dword v0, v[4:5], off
	v_ashrrev_i32_e32 v7, 31, v6
	v_lshlrev_b64 v[8:9], 4, v[6:7]
	v_lshl_add_u64 v[6:7], s[8:9], 0, v[8:9]
	v_lshl_add_u64 v[8:9], s[10:11], 0, v[8:9]
	s_addk_i32 s18, 0x200
	s_add_u32 s16, s16, 0x20000
	s_addc_u32 s17, s17, 0
	s_add_u32 s14, s14, 0x400000
	s_addc_u32 s15, s15, 0
	s_add_u32 s10, s10, 0x800000
	s_addc_u32 s11, s11, 0
	s_cmp_lt_i32 s18, s30
	s_waitcnt vmcnt(0)
	s_nop 1
	v_mov_b32_dpp v4, v0 quad_perm:[1,0,3,2] row_mask:0xf bank_mask:0xf
	s_waitcnt lgkmcnt(0)
	v_add_f32_e32 v0, v0, v4
	s_nop 1
	v_mov_b32_dpp v4, v0 quad_perm:[2,3,0,1] row_mask:0xf bank_mask:0xf
	s_waitcnt lgkmcnt(0)
	v_add_f32_e32 v0, v0, v4
	s_nop 1
	v_mov_b32_dpp v4, v0 row_shl:4 row_mask:0xf bank_mask:0x5
	v_mov_b32_dpp v4, v0 row_shr:4 row_mask:0xf bank_mask:0xa
	s_waitcnt lgkmcnt(0)
	v_add_f32_e32 v0, v0, v4
	s_nop 1
	v_mov_b32_dpp v4, v0 row_ror:8 row_mask:0xf bank_mask:0xf
	s_waitcnt lgkmcnt(0)
	v_add_f32_e32 v0, v0, v4
	ds_swizzle_b32 v4, v0 offset:swizzle(SWAP,16)
	s_waitcnt lgkmcnt(0)
	v_add_f32_e32 v0, v0, v4
	v_mov_b32_e32 v4, v0
	s_nop 1
	v_permlane32_swap_b32_e32 v0, v4
	v_add_f32_e32 v0, v0, v4
	v_fmamk_f32 v0, v0, 0x39800000, v214
	v_cmp_gt_f32_e32 vcc, s29, v0
	v_mul_f32_e32 v4, 0x4f800000, v0
	s_nop 0
	v_cndmask_b32_e32 v0, v0, v4, vcc
	v_sqrt_f32_e32 v4, v0
	s_nop 0
	v_add_u32_e32 v5, -1, v4
	v_fma_f32 v10, -v5, v4, v0
	v_cmp_ge_f32_e64 s[6:7], 0, v10
	v_add_u32_e32 v10, 1, v4
	s_nop 0
	v_cndmask_b32_e64 v5, v4, v5, s[6:7]
	v_fma_f32 v4, -v10, v4, v0
	v_cmp_lt_f32_e64 s[6:7], 0, v4
	s_nop 1
	v_cndmask_b32_e64 v4, v5, v10, s[6:7]
	v_mul_f32_e32 v5, 0x37800000, v4
	v_cndmask_b32_e32 v4, v4, v5, vcc
	v_cmp_class_f32_e32 vcc, v0, v252
	s_nop 1
	v_cndmask_b32_e32 v0, v4, v0, vcc
	v_div_scale_f32 v4, s[6:7], v0, v0, 1.0
	v_rcp_f32_e32 v5, v4
	s_mov_b32 s6, 0x22600000
	v_fma_f32 v10, -v4, v5, 1.0
	v_fmac_f32_e32 v5, v10, v5
	v_div_scale_f32 v10, vcc, 1.0, v0, 1.0
	v_mul_f32_e32 v11, v10, v5
	v_fma_f32 v12, -v4, v11, v10
	v_fmac_f32_e32 v11, v12, v5
	v_fma_f32 v4, -v4, v11, v10
	v_div_fmas_f32 v4, v4, v5, v11
	v_add_co_u32_e32 v20, vcc, s6, v2
	v_div_fixup_f32 v0, v4, v0, 1.0
	s_nop 0
	v_addc_co_u32_e32 v21, vcc, 0, v3, vcc
	v_add_co_u32_e32 v10, vcc, s28, v2
	v_mov_b32_e32 v4, 0x7fc00000
	s_nop 0
	v_addc_co_u32_e32 v11, vcc, 0, v3, vcc
	v_cndmask_b32_e64 v0, v4, v0, s[4:5]
	global_load_dwordx4 v[2:5], v[10:11], off offset:-4096
	global_load_dwordx4 v[12:15], v[6:7], off offset:16
	global_load_dwordx4 v[16:19], v[6:7], off
	s_mov_b64 s[6:7], 0x2000
	s_waitcnt vmcnt(2)
	v_lshlrev_b32_e32 v24, 16, v2
	v_and_b32_e32 v25, 0xffff0000, v2
	v_lshlrev_b32_e32 v2, 16, v3
	v_and_b32_e32 v3, 0xffff0000, v3
	v_pk_mul_f32 v[2:3], v[0:1], v[2:3] op_sel_hi:[0,1]
	s_waitcnt vmcnt(0)
	v_pk_mul_f32 v[18:19], v[18:19], v[2:3]
	v_lshlrev_b32_e32 v2, 16, v4
	v_and_b32_e32 v3, 0xffff0000, v4
	v_lshlrev_b32_e32 v4, 16, v5
	v_and_b32_e32 v5, 0xffff0000, v5
	v_pk_mul_f32 v[24:25], v[0:1], v[24:25] op_sel_hi:[0,1]
	v_pk_mul_f32 v[2:3], v[0:1], v[2:3] op_sel_hi:[0,1]
	v_pk_mul_f32 v[4:5], v[0:1], v[4:5] op_sel_hi:[0,1]
	v_pk_mul_f32 v[16:17], v[16:17], v[24:25]
	v_pk_mul_f32 v[4:5], v[14:15], v[4:5]
	v_pk_mul_f32 v[2:3], v[12:13], v[2:3]
	global_store_dwordx4 v[8:9], v[16:19], off
	global_store_dwordx4 v[8:9], v[2:5], off offset:16
	global_load_dwordx4 v[2:5], v[20:21], off offset:1024
	s_nop 0
	global_load_dwordx4 v[12:15], v[6:7], off offset:2064
	global_load_dwordx4 v[16:19], v[6:7], off offset:2048
	s_waitcnt vmcnt(2)
	v_lshlrev_b32_e32 v24, 16, v2
	v_and_b32_e32 v25, 0xffff0000, v2
	v_lshlrev_b32_e32 v2, 16, v3
	v_and_b32_e32 v3, 0xffff0000, v3
	v_pk_mul_f32 v[2:3], v[0:1], v[2:3] op_sel_hi:[0,1]
	s_waitcnt vmcnt(0)
	v_pk_mul_f32 v[18:19], v[18:19], v[2:3]
	v_lshlrev_b32_e32 v2, 16, v4
	v_and_b32_e32 v3, 0xffff0000, v4
	v_lshlrev_b32_e32 v4, 16, v5
	v_and_b32_e32 v5, 0xffff0000, v5
	v_pk_mul_f32 v[24:25], v[0:1], v[24:25] op_sel_hi:[0,1]
	v_pk_mul_f32 v[2:3], v[0:1], v[2:3] op_sel_hi:[0,1]
	v_pk_mul_f32 v[4:5], v[0:1], v[4:5] op_sel_hi:[0,1]
	v_pk_mul_f32 v[16:17], v[16:17], v[24:25]
	v_pk_mul_f32 v[4:5], v[14:15], v[4:5]
	v_pk_mul_f32 v[2:3], v[12:13], v[2:3]
	global_store_dwordx4 v[8:9], v[16:19], off offset:2048
	global_store_dwordx4 v[8:9], v[2:5], off offset:2064
	global_load_dwordx4 v[2:5], v[20:21], off offset:2048
	v_add_co_u32_e32 v16, vcc, s27, v6
	v_lshl_add_u64 v[14:15], v[6:7], 0, s[48:49]
	s_nop 0
	v_addc_co_u32_e32 v17, vcc, 0, v7, vcc
	v_add_co_u32_e32 v12, vcc, s34, v6
	s_nop 1
	v_addc_co_u32_e32 v13, vcc, 0, v7, vcc
	global_load_dwordx4 v[24:27], v[12:13], off offset:-4096
	global_load_dwordx4 v[28:31], v[14:15], off offset:16
	v_add_co_u32_e32 v18, vcc, s27, v8
	s_waitcnt vmcnt(2)
	v_lshlrev_b32_e32 v14, 16, v2
	v_and_b32_e32 v15, 0xffff0000, v2
	v_lshlrev_b32_e32 v2, 16, v3
	v_and_b32_e32 v3, 0xffff0000, v3
	v_pk_mul_f32 v[2:3], v[0:1], v[2:3] op_sel_hi:[0,1]
	v_pk_mul_f32 v[14:15], v[0:1], v[14:15] op_sel_hi:[0,1]
	v_addc_co_u32_e32 v19, vcc, 0, v9, vcc
	s_waitcnt vmcnt(1)
	v_pk_mul_f32 v[26:27], v[26:27], v[2:3]
	v_lshlrev_b32_e32 v2, 16, v4
	v_and_b32_e32 v3, 0xffff0000, v4
	v_lshlrev_b32_e32 v4, 16, v5
	v_and_b32_e32 v5, 0xffff0000, v5
	v_pk_mul_f32 v[24:25], v[24:25], v[14:15]
	v_add_co_u32_e32 v14, vcc, s34, v8
	v_pk_mul_f32 v[2:3], v[0:1], v[2:3] op_sel_hi:[0,1]
	v_pk_mul_f32 v[4:5], v[0:1], v[4:5] op_sel_hi:[0,1]
	v_addc_co_u32_e32 v15, vcc, 0, v9, vcc
	s_waitcnt vmcnt(0)
	v_pk_mul_f32 v[4:5], v[30:31], v[4:5]
	v_pk_mul_f32 v[2:3], v[28:29], v[2:3]
	global_store_dwordx4 v[14:15], v[24:27], off offset:-4096
	global_store_dwordx4 v[18:19], v[2:5], off offset:16
	global_load_dwordx4 v[2:5], v[20:21], off offset:3072
	v_lshl_add_u64 v[20:21], v[6:7], 0, s[50:51]
	global_load_dwordx4 v[24:27], v[16:17], off offset:2048
	global_load_dwordx4 v[28:31], v[20:21], off offset:16
	v_lshl_add_u64 v[20:21], v[6:7], 0, s[6:7]
	s_mov_b64 s[6:7], 0x2800
	s_waitcnt vmcnt(2)
	v_lshlrev_b32_e32 v16, 16, v2
	v_and_b32_e32 v17, 0xffff0000, v2
	v_lshlrev_b32_e32 v2, 16, v3
	v_and_b32_e32 v3, 0xffff0000, v3
	v_pk_mul_f32 v[2:3], v[0:1], v[2:3] op_sel_hi:[0,1]
	s_waitcnt vmcnt(1)
	v_pk_mul_f32 v[26:27], v[26:27], v[2:3]
	v_lshlrev_b32_e32 v2, 16, v4
	v_and_b32_e32 v3, 0xffff0000, v4
	v_lshlrev_b32_e32 v4, 16, v5
	v_and_b32_e32 v5, 0xffff0000, v5
	v_pk_mul_f32 v[16:17], v[0:1], v[16:17] op_sel_hi:[0,1]
	v_pk_mul_f32 v[2:3], v[0:1], v[2:3] op_sel_hi:[0,1]
	v_pk_mul_f32 v[4:5], v[0:1], v[4:5] op_sel_hi:[0,1]
	v_pk_mul_f32 v[24:25], v[24:25], v[16:17]
	s_waitcnt vmcnt(0)
	v_pk_mul_f32 v[4:5], v[30:31], v[4:5]
	v_pk_mul_f32 v[2:3], v[28:29], v[2:3]
	global_store_dwordx4 v[18:19], v[24:27], off offset:2048
	global_store_dwordx4 v[18:19], v[2:5], off offset:2064
	global_load_dwordx4 v[2:5], v[10:11], off
	s_nop 0
	global_load_dwordx4 v[16:19], v[12:13], off
	global_load_dwordx4 v[24:27], v[20:21], off offset:16
	s_waitcnt vmcnt(2)
	v_lshlrev_b32_e32 v20, 16, v2
	v_and_b32_e32 v21, 0xffff0000, v2
	v_lshlrev_b32_e32 v2, 16, v3
	v_and_b32_e32 v3, 0xffff0000, v3
	v_pk_mul_f32 v[2:3], v[0:1], v[2:3] op_sel_hi:[0,1]
	s_waitcnt vmcnt(1)
	v_pk_mul_f32 v[18:19], v[18:19], v[2:3]
	v_lshlrev_b32_e32 v2, 16, v4
	v_and_b32_e32 v3, 0xffff0000, v4
	v_lshlrev_b32_e32 v4, 16, v5
	v_and_b32_e32 v5, 0xffff0000, v5
	v_pk_mul_f32 v[20:21], v[0:1], v[20:21] op_sel_hi:[0,1]
	v_pk_mul_f32 v[2:3], v[0:1], v[2:3] op_sel_hi:[0,1]
	v_pk_mul_f32 v[4:5], v[0:1], v[4:5] op_sel_hi:[0,1]
	v_pk_mul_f32 v[16:17], v[16:17], v[20:21]
	s_waitcnt vmcnt(0)
	v_pk_mul_f32 v[4:5], v[26:27], v[4:5]
	v_pk_mul_f32 v[2:3], v[24:25], v[2:3]
	global_store_dwordx4 v[14:15], v[16:19], off
	global_store_dwordx4 v[14:15], v[2:5], off offset:16
	global_load_dwordx4 v[2:5], v[10:11], off offset:1024
	v_lshl_add_u64 v[20:21], v[6:7], 0, s[6:7]
	global_load_dwordx4 v[16:19], v[12:13], off offset:2048
	global_load_dwordx4 v[24:27], v[20:21], off offset:16
	s_mov_b64 s[6:7], 0x3000
	s_waitcnt vmcnt(2)
	v_lshlrev_b32_e32 v12, 16, v2
	v_and_b32_e32 v13, 0xffff0000, v2
	v_lshlrev_b32_e32 v2, 16, v3
	v_and_b32_e32 v3, 0xffff0000, v3
	v_pk_mul_f32 v[2:3], v[0:1], v[2:3] op_sel_hi:[0,1]
	s_waitcnt vmcnt(1)
	v_pk_mul_f32 v[18:19], v[18:19], v[2:3]
	v_lshlrev_b32_e32 v2, 16, v4
	v_and_b32_e32 v3, 0xffff0000, v4
	v_lshlrev_b32_e32 v4, 16, v5
	v_and_b32_e32 v5, 0xffff0000, v5
	v_pk_mul_f32 v[12:13], v[0:1], v[12:13] op_sel_hi:[0,1]
	v_pk_mul_f32 v[2:3], v[0:1], v[2:3] op_sel_hi:[0,1]
	v_pk_mul_f32 v[4:5], v[0:1], v[4:5] op_sel_hi:[0,1]
	v_pk_mul_f32 v[16:17], v[16:17], v[12:13]
	s_waitcnt vmcnt(0)
	v_pk_mul_f32 v[4:5], v[26:27], v[4:5]
	v_pk_mul_f32 v[2:3], v[24:25], v[2:3]
	global_store_dwordx4 v[14:15], v[16:19], off offset:2048
	global_store_dwordx4 v[14:15], v[2:5], off offset:2064
	global_load_dwordx4 v[12:15], v[10:11], off offset:2048
	s_nop 0
	v_add_co_u32_e32 v2, vcc, s35, v6
	v_lshl_add_u64 v[4:5], v[6:7], 0, s[6:7]
	s_nop 0
	v_addc_co_u32_e32 v3, vcc, 0, v7, vcc
	global_load_dwordx4 v[16:19], v[2:3], off
	global_load_dwordx4 v[24:27], v[4:5], off offset:16
	v_add_co_u32_e32 v20, vcc, s35, v8
	s_mov_b64 s[6:7], 0x3800
	s_nop 0
	v_addc_co_u32_e32 v21, vcc, 0, v9, vcc
	v_lshl_add_u64 v[6:7], v[6:7], 0, s[6:7]
	s_waitcnt vmcnt(2)
	v_lshlrev_b32_e32 v4, 16, v12
	v_and_b32_e32 v5, 0xffff0000, v12
	v_pk_mul_f32 v[4:5], v[0:1], v[4:5] op_sel_hi:[0,1]
	v_lshlrev_b32_e32 v12, 16, v13
	v_and_b32_e32 v13, 0xffff0000, v13
	v_lshlrev_b32_e32 v8, 16, v15
	s_waitcnt vmcnt(1)
	v_pk_mul_f32 v[16:17], v[16:17], v[4:5]
	v_lshlrev_b32_e32 v4, 16, v14
	v_and_b32_e32 v5, 0xffff0000, v14
	v_and_b32_e32 v9, 0xffff0000, v15
	v_pk_mul_f32 v[12:13], v[0:1], v[12:13] op_sel_hi:[0,1]
	v_pk_mul_f32 v[4:5], v[0:1], v[4:5] op_sel_hi:[0,1]
	v_pk_mul_f32 v[8:9], v[0:1], v[8:9] op_sel_hi:[0,1]
	v_pk_mul_f32 v[18:19], v[18:19], v[12:13]
	s_waitcnt vmcnt(0)
	v_pk_mul_f32 v[14:15], v[26:27], v[8:9]
	v_pk_mul_f32 v[12:13], v[24:25], v[4:5]
	global_store_dwordx4 v[20:21], v[16:19], off
	global_store_dwordx4 v[20:21], v[12:15], off offset:16
	global_load_dwordx4 v[8:11], v[10:11], off offset:3072
	s_nop 0
	global_load_dwordx4 v[2:5], v[2:3], off offset:2048
	s_nop 0
	global_load_dwordx4 v[12:15], v[6:7], off offset:16
	s_waitcnt vmcnt(2)
	v_lshlrev_b32_e32 v6, 16, v8
	v_and_b32_e32 v7, 0xffff0000, v8
	v_lshlrev_b32_e32 v8, 16, v9
	v_and_b32_e32 v9, 0xffff0000, v9
	v_pk_mul_f32 v[6:7], v[0:1], v[6:7] op_sel_hi:[0,1]
	v_pk_mul_f32 v[8:9], v[0:1], v[8:9] op_sel_hi:[0,1]
	s_waitcnt vmcnt(1)
	v_pk_mul_f32 v[4:5], v[4:5], v[8:9]
	v_pk_mul_f32 v[2:3], v[2:3], v[6:7]
	global_store_dwordx4 v[20:21], v[2:5], off offset:2048
	s_nop 1
	v_lshlrev_b32_e32 v2, 16, v10
	v_and_b32_e32 v3, 0xffff0000, v10
	v_lshlrev_b32_e32 v4, 16, v11
	v_and_b32_e32 v5, 0xffff0000, v11
	v_pk_mul_f32 v[2:3], v[0:1], v[2:3] op_sel_hi:[0,1]
	v_pk_mul_f32 v[4:5], v[0:1], v[4:5] op_sel_hi:[0,1]
	s_waitcnt vmcnt(1)
	v_pk_mul_f32 v[4:5], v[14:15], v[4:5]
	v_pk_mul_f32 v[2:3], v[12:13], v[2:3]
	global_store_dwordx4 v[20:21], v[2:5], off offset:2064
	s_cbranch_scc1 .LBB0_1363
	s_getpc_b64 s[98:99]
